# GEMM K-loops: barrier skewed two MFMA groups early, next step's first fragment reads issued before the last two groups
# speedup vs baseline: 1.2729x; 1.0260x over previous
; template <int EPI>
; DI bool tile_coords(int j, int mpx, int& m0, int& n0) {
;     ...
;   } else {
;     if (q >= mpx * 4) return false;
;     m0 = (x * mpx + (q >> 2)) * 256;
;     n0 = (q & 3) * 256;
;   }
; template <int EPI>
; DI void gemm_phase(const P& p, int l, const u16* __restrict__ A, const u16* __restrict__ Bt, int mpx, char* lds) {
;     ...
;   while (true) {
;   const int tn = t + 1;
;   int m1 = 0, n1 = 0;
;   const bool has_next = tile_coords<EPI>(tn, mpx, m1, n1);
;   const u16* Agn = A + (size_t)m1 * 1024;
;   const u16* Bgn = Bt + (size_t)n1 * 1024;
;   f32x4 acc[8][4];
; #pragma unroll
;   for (int i = 0; i < 8; ++i)
; #pragma unroll
;     for (int j = 0; j < 4; ++j) acc[i][j] = zero4();
;   {
;   const int lane = tid & 63, w = tid >> 6, r = lane & 15, g = lane >> 4, wm = w >> 2, wn = w & 3;
;   __syncthreads();
;   GLOAD(Ag, Bg, 64)
;   __builtin_amdgcn_sched_barrier(0);
;   GCOMPUTE_KS(As0, Bs0, 0)
;   __builtin_amdgcn_sched_barrier(0);
;   GSTORE(As1, Bs1)
;   GLOAD(Ag, Bg, 128)
;   __builtin_amdgcn_sched_barrier(0);
;   GCOMPUTE_KS(As0, Bs0, 1)
.LBB0_69:
	v_lshl_add_u64 v[94:95], s[48:49], 0, v[196:197]
	v_add_co_u32_e32 v96, vcc, s33, v94
	v_lshl_add_u64 v[102:103], s[46:47], 0, v[196:197]
	s_nop 0
	v_addc_co_u32_e32 v97, vcc, 0, v95, vcc
	v_add_co_u32_e32 v98, vcc, s35, v94
	s_waitcnt lgkmcnt(0)
	s_nop 0
	v_addc_co_u32_e32 v99, vcc, 0, v95, vcc
	v_add_co_u32_e32 v100, vcc, s39, v94
	s_barrier
	s_nop 0
	v_addc_co_u32_e32 v101, vcc, 0, v95, vcc
	v_add_co_u32_e32 v104, vcc, s33, v102
	s_nop 1
	v_addc_co_u32_e32 v105, vcc, 0, v103, vcc
	v_add_co_u32_e32 v106, vcc, s35, v102
	global_load_dwordx4 v[2:5], v[94:95], off offset:128
	global_load_dwordx4 v[6:9], v[96:97], off offset:128
	v_addc_co_u32_e32 v107, vcc, 0, v103, vcc
	v_add_co_u32_e32 v110, vcc, s39, v102
	global_load_dwordx4 v[10:13], v[98:99], off offset:128
	global_load_dwordx4 v[14:17], v[100:101], off offset:128
	global_load_dwordx4 v[18:21], v[102:103], off offset:128
	global_load_dwordx4 v[22:25], v[104:105], off offset:128
	v_addc_co_u32_e32 v111, vcc, 0, v103, vcc
	global_load_dwordx4 v[26:29], v[106:107], off offset:128
	global_load_dwordx4 v[30:33], v[110:111], off offset:128
	s_add_i32 s56, s56, 1
	s_mul_i32 s2, s56, s57
	s_add_i32 s2, s2, s84
	s_cmp_ge_u32 s2, s25
	s_cselect_b64 s[40:41], -1, 0
	s_lshr_b32 s42, s2, 2
	s_add_i32 s42, s42, s51
	s_lshl_b32 s58, s42, 8
	s_lshl_b32 s42, s2, 8
	s_and_b32 s59, s42, 0x300
	s_lshl_b32 s42, s59, 11
	s_cmp_lt_u32 s2, s25
	s_cselect_b32 s2, s58, 0
	s_cselect_b32 s44, s42, 0
	s_lshl_b64 s[42:43], s[2:3], 11
	s_add_u32 s42, s16, s42
	s_mov_b32 s64, 1
	s_addc_u32 s43, s17, s43
	ds_read_b128 v[34:37], v227
	ds_read_b128 v[38:41], v207 offset:32768
	ds_read_b128 v[42:45], v207 offset:34816
	ds_read_b128 v[46:49], v227 offset:2048
	ds_read_b128 v[58:61], v207 offset:36864
	ds_read_b128 v[62:65], v207 offset:38912
	ds_read_b128 v[82:85], v227 offset:4096
	ds_read_b128 v[86:89], v227 offset:6144
	s_waitcnt lgkmcnt(6)
	v_mfma_f32_16x16x32_bf16 v[50:53], v[34:37], v[38:41], 0
	s_add_u32 s44, s26, s44
	s_addc_u32 s45, s27, 0
	s_waitcnt lgkmcnt(0)
	v_mfma_f32_16x16x32_bf16 v[126:129], v[86:89], v[38:41], 0
	v_mfma_f32_16x16x32_bf16 v[130:133], v[86:89], v[42:45], 0
	v_mfma_f32_16x16x32_bf16 v[134:137], v[86:89], v[58:61], 0
	v_mfma_f32_16x16x32_bf16 v[138:141], v[86:89], v[62:65], 0
	ds_read_b128 v[86:89], v227 offset:8192
	ds_read_b128 v[90:93], v227 offset:10240
	s_waitcnt lgkmcnt(1)
	v_mfma_f32_16x16x32_bf16 v[142:145], v[86:89], v[38:41], 0
	v_mfma_f32_16x16x32_bf16 v[146:149], v[86:89], v[42:45], 0
	v_mfma_f32_16x16x32_bf16 v[150:153], v[86:89], v[58:61], 0
	v_mfma_f32_16x16x32_bf16 v[154:157], v[86:89], v[62:65], 0
	s_waitcnt lgkmcnt(0)
	v_mfma_f32_16x16x32_bf16 v[158:161], v[90:93], v[38:41], 0
	v_mfma_f32_16x16x32_bf16 v[162:165], v[90:93], v[42:45], 0
	v_mfma_f32_16x16x32_bf16 v[166:169], v[90:93], v[58:61], 0
	v_mfma_f32_16x16x32_bf16 v[170:173], v[90:93], v[62:65], 0
	ds_read_b128 v[86:89], v227 offset:12288
	ds_read_b128 v[90:93], v227 offset:14336
	v_mfma_f32_16x16x32_bf16 v[54:57], v[34:37], v[42:45], 0
	v_mfma_f32_16x16x32_bf16 v[66:69], v[34:37], v[58:61], 0
	v_mfma_f32_16x16x32_bf16 v[34:37], v[34:37], v[62:65], 0
	v_mfma_f32_16x16x32_bf16 v[70:73], v[46:49], v[38:41], 0
	v_mfma_f32_16x16x32_bf16 v[74:77], v[46:49], v[42:45], 0
	v_mfma_f32_16x16x32_bf16 v[78:81], v[46:49], v[58:61], 0
	v_mfma_f32_16x16x32_bf16 v[46:49], v[46:49], v[62:65], 0
	v_mfma_f32_16x16x32_bf16 v[114:117], v[82:85], v[38:41], 0
	v_mfma_f32_16x16x32_bf16 v[118:121], v[82:85], v[42:45], 0
	v_mfma_f32_16x16x32_bf16 v[122:125], v[82:85], v[58:61], 0
	v_mfma_f32_16x16x32_bf16 v[82:85], v[82:85], v[62:65], 0
	s_waitcnt lgkmcnt(1)
	v_mfma_f32_16x16x32_bf16 v[174:177], v[86:89], v[38:41], 0
	v_mfma_f32_16x16x32_bf16 v[178:181], v[86:89], v[42:45], 0
	v_mfma_f32_16x16x32_bf16 v[182:185], v[86:89], v[58:61], 0
	v_mfma_f32_16x16x32_bf16 v[186:189], v[86:89], v[62:65], 0
	s_waitcnt lgkmcnt(0)
	v_mfma_f32_16x16x32_bf16 v[190:193], v[90:93], v[38:41], 0
	v_mfma_f32_16x16x32_bf16 v[212:215], v[90:93], v[42:45], 0
	v_mfma_f32_16x16x32_bf16 v[216:219], v[90:93], v[58:61], 0
	v_mfma_f32_16x16x32_bf16 v[220:223], v[90:93], v[62:65], 0
	s_waitcnt vmcnt(7)
	ds_write_b128 v199, v[2:5]
	s_waitcnt vmcnt(6)
	ds_write_b128 v200, v[6:9]
	s_waitcnt vmcnt(5)
	ds_write_b128 v201, v[10:13]
	s_waitcnt vmcnt(4)
	ds_write_b128 v202, v[14:17]
	s_waitcnt vmcnt(3)
	ds_write_b128 v203, v[18:21]
	s_waitcnt vmcnt(2)
	ds_write_b128 v204, v[22:25]
	s_waitcnt vmcnt(1)
	ds_write_b128 v205, v[26:29]
	s_waitcnt vmcnt(0)
	ds_write_b128 v206, v[30:33]
	global_load_dwordx4 v[18:21], v[94:95], off offset:256
	global_load_dwordx4 v[86:89], v[96:97], off offset:256
	global_load_dwordx4 v[90:93], v[98:99], off offset:256
	s_nop 0
	global_load_dwordx4 v[94:97], v[100:101], off offset:256
	s_nop 0
	global_load_dwordx4 v[98:101], v[102:103], off offset:256
	s_nop 0
	global_load_dwordx4 v[102:105], v[104:105], off offset:256
	s_nop 0
	global_load_dwordx4 v[106:109], v[106:107], off offset:256
	s_nop 0
	global_load_dwordx4 v[110:113], v[110:111], off offset:256
	ds_read_b128 v[2:5], v229
	ds_read_b128 v[234:237], v228 offset:32768
	ds_read_b128 v[238:241], v228 offset:34816
	ds_read_b128 v[242:245], v228 offset:36864
	ds_read_b128 v[246:249], v228 offset:38912
	s_waitcnt lgkmcnt(3)
	v_mfma_f32_16x16x32_bf16 v[6:9], v[2:5], v[234:237], v[50:53]
	s_waitcnt lgkmcnt(2)
	v_mfma_f32_16x16x32_bf16 v[10:13], v[2:5], v[238:241], v[54:57]
	s_waitcnt lgkmcnt(1)
	v_mfma_f32_16x16x32_bf16 v[14:17], v[2:5], v[242:245], v[66:69]
	s_waitcnt lgkmcnt(0)
	v_mfma_f32_16x16x32_bf16 v[22:25], v[2:5], v[246:249], v[34:37]
	ds_read_b128 v[2:5], v229 offset:2048
	s_waitcnt lgkmcnt(0)
; #define GCOMPUTE(AS, BS) GCOMPUTE_KS(AS, BS, 0) GCOMPUTE_KS(AS, BS, 1)
; template <int EPI>
; DI void gemm_phase(const P& p, int l, const u16* __restrict__ A, const u16* __restrict__ Bt, int mpx, char* lds) {
;     ...
;   GCOMPUTE_KS(As0, Bs0, 1)
;   __builtin_amdgcn_sched_barrier(0);
; #pragma unroll 1
;   for (int kk = 1; kk < 15; kk += 2) {
;     __syncthreads();
;     GSTORE(As0, Bs0)
;     GLOAD(Ag, Bg, (kk + 2) * 64)
;     __builtin_amdgcn_sched_barrier(0);
;     GCOMPUTE(As1, Bs1)
;     __builtin_amdgcn_sched_barrier(0);
;     __syncthreads();
;     GSTORE(As1, Bs1)
;     {
;       const bool in_tile = kk + 3 < 16;
;       const u16* pa = in_tile ? Ag : Agn;
;       const u16* pb = in_tile ? Bg : Bgn;
;       const int k0 = in_tile ? (kk + 3) * 64 : 0;
;       GLOAD(pa, pb, k0)
;     }
;     __builtin_amdgcn_sched_barrier(0);
;     GCOMPUTE(As0, Bs0)
	v_mfma_f32_16x16x32_bf16 v[26:29], v[2:5], v[234:237], v[70:73]
	v_mfma_f32_16x16x32_bf16 v[30:33], v[2:5], v[238:241], v[74:77]
	v_mfma_f32_16x16x32_bf16 v[34:37], v[2:5], v[242:245], v[78:81]
	v_mfma_f32_16x16x32_bf16 v[38:41], v[2:5], v[246:249], v[46:49]
	ds_read_b128 v[2:5], v229 offset:4096
	s_waitcnt lgkmcnt(0)
	v_mfma_f32_16x16x32_bf16 v[42:45], v[2:5], v[234:237], v[114:117]
	v_mfma_f32_16x16x32_bf16 v[46:49], v[2:5], v[238:241], v[118:121]
	v_mfma_f32_16x16x32_bf16 v[50:53], v[2:5], v[242:245], v[122:125]
	v_mfma_f32_16x16x32_bf16 v[54:57], v[2:5], v[246:249], v[82:85]
	ds_read_b128 v[2:5], v229 offset:6144
	s_waitcnt lgkmcnt(0)
	v_mfma_f32_16x16x32_bf16 v[58:61], v[2:5], v[234:237], v[126:129]
	v_mfma_f32_16x16x32_bf16 v[62:65], v[2:5], v[238:241], v[130:133]
	v_mfma_f32_16x16x32_bf16 v[66:69], v[2:5], v[242:245], v[134:137]
	v_mfma_f32_16x16x32_bf16 v[70:73], v[2:5], v[246:249], v[138:141]
	ds_read_b128 v[2:5], v229 offset:8192
	s_waitcnt lgkmcnt(0)
	v_mfma_f32_16x16x32_bf16 v[74:77], v[2:5], v[234:237], v[142:145]
	v_mfma_f32_16x16x32_bf16 v[78:81], v[2:5], v[238:241], v[146:149]
	v_mfma_f32_16x16x32_bf16 v[82:85], v[2:5], v[242:245], v[150:153]
	v_mfma_f32_16x16x32_bf16 v[114:117], v[2:5], v[246:249], v[154:157]
	ds_read_b128 v[2:5], v229 offset:10240
	s_waitcnt lgkmcnt(0)
	v_mfma_f32_16x16x32_bf16 v[118:121], v[2:5], v[234:237], v[158:161]
	v_mfma_f32_16x16x32_bf16 v[122:125], v[2:5], v[238:241], v[162:165]
	v_mfma_f32_16x16x32_bf16 v[126:129], v[2:5], v[242:245], v[166:169]
	v_mfma_f32_16x16x32_bf16 v[130:133], v[2:5], v[246:249], v[170:173]
	ds_read_b128 v[2:5], v229 offset:12288
	s_waitcnt lgkmcnt(0)
	v_mfma_f32_16x16x32_bf16 v[134:137], v[2:5], v[234:237], v[174:177]
	v_mfma_f32_16x16x32_bf16 v[138:141], v[2:5], v[238:241], v[178:181]
	v_mfma_f32_16x16x32_bf16 v[142:145], v[2:5], v[242:245], v[182:185]
	v_mfma_f32_16x16x32_bf16 v[146:149], v[2:5], v[246:249], v[186:189]
	ds_read_b128 v[2:5], v229 offset:14336
	s_waitcnt lgkmcnt(0)
	v_mfma_f32_16x16x32_bf16 v[150:153], v[2:5], v[234:237], v[190:193]
	v_mfma_f32_16x16x32_bf16 v[154:157], v[2:5], v[238:241], v[212:215]
	v_mfma_f32_16x16x32_bf16 v[158:161], v[2:5], v[242:245], v[216:219]
	v_mfma_f32_16x16x32_bf16 v[2:5], v[2:5], v[246:249], v[220:223]
	s_movk_i32 s62, 0x100
	s_mov_b64 s[52:53], s[46:47]
	s_mov_b64 s[54:55], s[48:49]
	v_add_u32_e32 v208, s33, v196
	v_add_u32_e32 v209, s35, v196
	v_add_u32_e32 v210, s39, v196
	s_barrier
	ds_read_b128 v[212:215], v230
	ds_read_b128 v[216:219], v230 offset:2048
	ds_read_b128 v[220:223], v230 offset:4096
	ds_read_b128 v[234:237], v230 offset:6144
	ds_read_b128 v[238:241], v231
	ds_read_b128 v[242:245], v231 offset:2048
	ds_read_b128 v[246:249], v231 offset:4096
	ds_read_b128 v[250:253], v231 offset:6144
	global_load_dwordx4 v[162:165], v196, s[54:55] offset:384
	global_load_dwordx4 v[166:169], v208, s[54:55] offset:384
	global_load_dwordx4 v[170:173], v209, s[54:55] offset:384
	global_load_dwordx4 v[174:177], v210, s[54:55] offset:384
	global_load_dwordx4 v[178:181], v196, s[52:53] offset:384
	global_load_dwordx4 v[182:185], v208, s[52:53] offset:384
	global_load_dwordx4 v[186:189], v209, s[52:53] offset:384
	global_load_dwordx4 v[190:193], v210, s[52:53] offset:384
.LBB0_70:
	s_add_i32 s63, s64, 2
	s_waitcnt lgkmcnt(3)
	v_mfma_f32_16x16x32_bf16 v[6:9], v[238:241], v[212:215], v[6:9]
	v_mfma_f32_16x16x32_bf16 v[10:13], v[238:241], v[216:219], v[10:13]
	v_mfma_f32_16x16x32_bf16 v[14:17], v[238:241], v[220:223], v[14:17]
	v_mfma_f32_16x16x32_bf16 v[22:25], v[238:241], v[234:237], v[22:25]
	ds_read_b128 v[238:241], v231 offset:8192
	s_waitcnt vmcnt(15)
	ds_write_b128 v198, v[18:21]
	s_waitcnt lgkmcnt(4)
	v_mfma_f32_16x16x32_bf16 v[26:29], v[242:245], v[212:215], v[26:29]
	v_mfma_f32_16x16x32_bf16 v[30:33], v[242:245], v[216:219], v[30:33]
	v_mfma_f32_16x16x32_bf16 v[34:37], v[242:245], v[220:223], v[34:37]
	v_mfma_f32_16x16x32_bf16 v[38:41], v[242:245], v[234:237], v[38:41]
	ds_read_b128 v[242:245], v231 offset:10240
	s_waitcnt vmcnt(14)
	ds_write_b128 v198, v[86:89] offset:8192
	ds_read_b128 v[18:21], v232
	s_waitcnt lgkmcnt(6)
	v_mfma_f32_16x16x32_bf16 v[42:45], v[246:249], v[212:215], v[42:45]
	v_mfma_f32_16x16x32_bf16 v[46:49], v[246:249], v[216:219], v[46:49]
	v_mfma_f32_16x16x32_bf16 v[50:53], v[246:249], v[220:223], v[50:53]
	v_mfma_f32_16x16x32_bf16 v[54:57], v[246:249], v[234:237], v[54:57]
	ds_read_b128 v[246:249], v231 offset:12288
	s_waitcnt vmcnt(13)
	ds_write_b128 v198, v[90:93] offset:16384
	ds_read_b128 v[86:89], v232 offset:2048
	s_waitcnt lgkmcnt(8)
	v_mfma_f32_16x16x32_bf16 v[58:61], v[250:253], v[212:215], v[58:61]
	v_mfma_f32_16x16x32_bf16 v[62:65], v[250:253], v[216:219], v[62:65]
	v_mfma_f32_16x16x32_bf16 v[66:69], v[250:253], v[220:223], v[66:69]
	v_mfma_f32_16x16x32_bf16 v[70:73], v[250:253], v[234:237], v[70:73]
	ds_read_b128 v[250:253], v231 offset:14336
	s_waitcnt vmcnt(12)
	ds_write_b128 v198, v[94:97] offset:24576
	ds_read_b128 v[90:93], v232 offset:4096
	s_waitcnt lgkmcnt(10)
	v_mfma_f32_16x16x32_bf16 v[74:77], v[238:241], v[212:215], v[74:77]
	v_mfma_f32_16x16x32_bf16 v[78:81], v[238:241], v[216:219], v[78:81]
	v_mfma_f32_16x16x32_bf16 v[82:85], v[238:241], v[220:223], v[82:85]
	v_mfma_f32_16x16x32_bf16 v[114:117], v[238:241], v[234:237], v[114:117]
	ds_read_b128 v[238:241], v233
	s_waitcnt vmcnt(11)
	ds_write_b128 v198, v[98:101] offset:32768
	ds_read_b128 v[94:97], v232 offset:6144
	s_waitcnt lgkmcnt(11)
	v_mfma_f32_16x16x32_bf16 v[118:121], v[242:245], v[212:215], v[118:121]
	v_mfma_f32_16x16x32_bf16 v[122:125], v[242:245], v[216:219], v[122:125]
	v_mfma_f32_16x16x32_bf16 v[126:129], v[242:245], v[220:223], v[126:129]
	v_mfma_f32_16x16x32_bf16 v[130:133], v[242:245], v[234:237], v[130:133]
	ds_read_b128 v[242:245], v233 offset:2048
	s_waitcnt vmcnt(10)
; #define GCOMPUTE(AS, BS) GCOMPUTE_KS(AS, BS, 0) GCOMPUTE_KS(AS, BS, 1)
; template <int EPI>
; DI void gemm_phase(const P& p, int l, const u16* __restrict__ A, const u16* __restrict__ Bt, int mpx, char* lds) {
;     ...
;   for (int kk = 1; kk < 15; kk += 2) {
;     __syncthreads();
;     GSTORE(As0, Bs0)
;     GLOAD(Ag, Bg, (kk + 2) * 64)
;     __builtin_amdgcn_sched_barrier(0);
;     GCOMPUTE(As1, Bs1)
;     __builtin_amdgcn_sched_barrier(0);
;     __syncthreads();
;     GSTORE(As1, Bs1)
;     {
;       const bool in_tile = kk + 3 < 16;
;       const u16* pa = in_tile ? Ag : Agn;
;       const u16* pb = in_tile ? Bg : Bgn;
;       const int k0 = in_tile ? (kk + 3) * 64 : 0;
;       GLOAD(pa, pb, k0)
;     }
;     __builtin_amdgcn_sched_barrier(0);
;     GCOMPUTE(As0, Bs0)
	ds_write_b128 v198, v[102:105] offset:40960
	s_waitcnt lgkmcnt(10)
	v_mfma_f32_16x16x32_bf16 v[134:137], v[246:249], v[212:215], v[134:137]
	v_mfma_f32_16x16x32_bf16 v[138:141], v[246:249], v[216:219], v[138:141]
	v_mfma_f32_16x16x32_bf16 v[142:145], v[246:249], v[220:223], v[142:145]
	v_mfma_f32_16x16x32_bf16 v[146:149], v[246:249], v[234:237], v[146:149]
	ds_read_b128 v[246:249], v233 offset:4096
	s_waitcnt vmcnt(9)
	ds_write_b128 v198, v[106:109] offset:49152
	s_waitcnt lgkmcnt(9)
	v_mfma_f32_16x16x32_bf16 v[150:153], v[250:253], v[212:215], v[150:153]
	v_mfma_f32_16x16x32_bf16 v[154:157], v[250:253], v[216:219], v[154:157]
	v_mfma_f32_16x16x32_bf16 v[158:161], v[250:253], v[220:223], v[158:161]
	v_mfma_f32_16x16x32_bf16 v[2:5], v[250:253], v[234:237], v[2:5]
	ds_read_b128 v[250:253], v233 offset:6144
	s_waitcnt vmcnt(8)
	ds_write_b128 v198, v[110:113] offset:57344
	s_waitcnt lgkmcnt(6)
	v_mfma_f32_16x16x32_bf16 v[6:9], v[238:241], v[18:21], v[6:9]
	v_mfma_f32_16x16x32_bf16 v[10:13], v[238:241], v[86:89], v[10:13]
	v_mfma_f32_16x16x32_bf16 v[14:17], v[238:241], v[90:93], v[14:17]
	v_mfma_f32_16x16x32_bf16 v[22:25], v[238:241], v[94:97], v[22:25]
	ds_read_b128 v[238:241], v233 offset:8192
	s_waitcnt lgkmcnt(6)
	v_mfma_f32_16x16x32_bf16 v[26:29], v[242:245], v[18:21], v[26:29]
	v_mfma_f32_16x16x32_bf16 v[30:33], v[242:245], v[86:89], v[30:33]
	v_mfma_f32_16x16x32_bf16 v[34:37], v[242:245], v[90:93], v[34:37]
	v_mfma_f32_16x16x32_bf16 v[38:41], v[242:245], v[94:97], v[38:41]
	ds_read_b128 v[242:245], v233 offset:10240
	s_waitcnt lgkmcnt(5)
	v_mfma_f32_16x16x32_bf16 v[42:45], v[246:249], v[18:21], v[42:45]
	v_mfma_f32_16x16x32_bf16 v[46:49], v[246:249], v[86:89], v[46:49]
	v_mfma_f32_16x16x32_bf16 v[50:53], v[246:249], v[90:93], v[50:53]
	v_mfma_f32_16x16x32_bf16 v[54:57], v[246:249], v[94:97], v[54:57]
	ds_read_b128 v[246:249], v233 offset:12288
	s_waitcnt lgkmcnt(4)
	v_mfma_f32_16x16x32_bf16 v[58:61], v[250:253], v[18:21], v[58:61]
	v_mfma_f32_16x16x32_bf16 v[62:65], v[250:253], v[86:89], v[62:65]
	v_mfma_f32_16x16x32_bf16 v[66:69], v[250:253], v[90:93], v[66:69]
	v_mfma_f32_16x16x32_bf16 v[70:73], v[250:253], v[94:97], v[70:73]
	ds_read_b128 v[250:253], v233 offset:14336
	s_waitcnt lgkmcnt(3)
	v_mfma_f32_16x16x32_bf16 v[74:77], v[238:241], v[18:21], v[74:77]
	v_mfma_f32_16x16x32_bf16 v[78:81], v[238:241], v[86:89], v[78:81]
	v_mfma_f32_16x16x32_bf16 v[82:85], v[238:241], v[90:93], v[82:85]
	v_mfma_f32_16x16x32_bf16 v[114:117], v[238:241], v[94:97], v[114:117]
	s_waitcnt lgkmcnt(2)
	v_mfma_f32_16x16x32_bf16 v[118:121], v[242:245], v[18:21], v[118:121]
	v_mfma_f32_16x16x32_bf16 v[122:125], v[242:245], v[86:89], v[122:125]
	v_mfma_f32_16x16x32_bf16 v[126:129], v[242:245], v[90:93], v[126:129]
	v_mfma_f32_16x16x32_bf16 v[130:133], v[242:245], v[94:97], v[130:133]
	s_waitcnt lgkmcnt(0)
	s_cmp_lt_u32 s64, 13
	s_cselect_b64 s[66:67], -1, 0
	s_and_b64 s[66:67], s[66:67], exec
	s_cselect_b32 s2, s62, 0
	s_cselect_b32 s65, s49, s43
	s_cselect_b32 s68, s48, s42
	s_cselect_b32 s70, s47, s45
	s_cselect_b32 s71, s46, s44
	s_lshl_b64 s[66:67], s[2:3], 1
	s_add_u32 s68, s68, s66
	s_addc_u32 s69, s65, s67
	s_add_u32 s66, s71, s66
	s_addc_u32 s67, s70, s67
	s_barrier
	ds_read_b128 v[212:215], v207 offset:32768
	ds_read_b128 v[216:219], v207 offset:34816
	ds_read_b128 v[220:223], v207 offset:36864
	ds_read_b128 v[234:237], v207 offset:38912
	ds_read_b128 v[238:241], v227
	ds_read_b128 v[242:245], v227 offset:2048
	v_mfma_f32_16x16x32_bf16 v[134:137], v[246:249], v[18:21], v[134:137]
	v_mfma_f32_16x16x32_bf16 v[138:141], v[246:249], v[86:89], v[138:141]
	v_mfma_f32_16x16x32_bf16 v[142:145], v[246:249], v[90:93], v[142:145]
	v_mfma_f32_16x16x32_bf16 v[146:149], v[246:249], v[94:97], v[146:149]
	ds_read_b128 v[246:249], v227 offset:4096
	v_mfma_f32_16x16x32_bf16 v[150:153], v[250:253], v[18:21], v[150:153]
	v_mfma_f32_16x16x32_bf16 v[154:157], v[250:253], v[86:89], v[154:157]
	v_mfma_f32_16x16x32_bf16 v[158:161], v[250:253], v[90:93], v[158:161]
	v_mfma_f32_16x16x32_bf16 v[2:5], v[250:253], v[94:97], v[2:5]
	ds_read_b128 v[250:253], v227 offset:6144
	global_load_dwordx4 v[18:21], v196, s[68:69]
	global_load_dwordx4 v[86:89], v208, s[68:69]
	global_load_dwordx4 v[90:93], v209, s[68:69]
	global_load_dwordx4 v[94:97], v210, s[68:69]
	global_load_dwordx4 v[98:101], v196, s[66:67]
	global_load_dwordx4 v[102:105], v208, s[66:67]
	global_load_dwordx4 v[106:109], v209, s[66:67]
	global_load_dwordx4 v[110:113], v210, s[66:67]
	s_waitcnt lgkmcnt(3)
	v_mfma_f32_16x16x32_bf16 v[6:9], v[238:241], v[212:215], v[6:9]
	v_mfma_f32_16x16x32_bf16 v[10:13], v[238:241], v[216:219], v[10:13]
	v_mfma_f32_16x16x32_bf16 v[14:17], v[238:241], v[220:223], v[14:17]
	v_mfma_f32_16x16x32_bf16 v[22:25], v[238:241], v[234:237], v[22:25]
	ds_read_b128 v[238:241], v227 offset:8192
	s_waitcnt vmcnt(15)
	ds_write_b128 v199, v[162:165]
	s_waitcnt lgkmcnt(4)
	v_mfma_f32_16x16x32_bf16 v[26:29], v[242:245], v[212:215], v[26:29]
	v_mfma_f32_16x16x32_bf16 v[30:33], v[242:245], v[216:219], v[30:33]
	v_mfma_f32_16x16x32_bf16 v[34:37], v[242:245], v[220:223], v[34:37]
	v_mfma_f32_16x16x32_bf16 v[38:41], v[242:245], v[234:237], v[38:41]
	ds_read_b128 v[242:245], v227 offset:10240
	s_waitcnt vmcnt(14)
	ds_write_b128 v200, v[166:169]
	ds_read_b128 v[162:165], v228 offset:32768
	s_waitcnt lgkmcnt(6)
	v_mfma_f32_16x16x32_bf16 v[42:45], v[246:249], v[212:215], v[42:45]
	v_mfma_f32_16x16x32_bf16 v[46:49], v[246:249], v[216:219], v[46:49]
	v_mfma_f32_16x16x32_bf16 v[50:53], v[246:249], v[220:223], v[50:53]
	v_mfma_f32_16x16x32_bf16 v[54:57], v[246:249], v[234:237], v[54:57]
	ds_read_b128 v[246:249], v227 offset:12288
	s_waitcnt vmcnt(13)
; #define GCOMPUTE(AS, BS) GCOMPUTE_KS(AS, BS, 0) GCOMPUTE_KS(AS, BS, 1)
; template <int EPI>
; DI void gemm_phase(const P& p, int l, const u16* __restrict__ A, const u16* __restrict__ Bt, int mpx, char* lds) {
;     ...
;   for (int kk = 1; kk < 15; kk += 2) {
;     __syncthreads();
;     GSTORE(As0, Bs0)
;     GLOAD(Ag, Bg, (kk + 2) * 64)
;     __builtin_amdgcn_sched_barrier(0);
;     GCOMPUTE(As1, Bs1)
;     __builtin_amdgcn_sched_barrier(0);
;     __syncthreads();
;     GSTORE(As1, Bs1)
;     {
;       const bool in_tile = kk + 3 < 16;
;       const u16* pa = in_tile ? Ag : Agn;
;       const u16* pb = in_tile ? Bg : Bgn;
;       const int k0 = in_tile ? (kk + 3) * 64 : 0;
;       GLOAD(pa, pb, k0)
;     }
;     __builtin_amdgcn_sched_barrier(0);
;     GCOMPUTE(As0, Bs0)
;     __builtin_amdgcn_sched_barrier(0);
;   }
	ds_write_b128 v201, v[170:173]
	ds_read_b128 v[166:169], v228 offset:34816
	s_waitcnt lgkmcnt(8)
	v_mfma_f32_16x16x32_bf16 v[58:61], v[250:253], v[212:215], v[58:61]
	v_mfma_f32_16x16x32_bf16 v[62:65], v[250:253], v[216:219], v[62:65]
	v_mfma_f32_16x16x32_bf16 v[66:69], v[250:253], v[220:223], v[66:69]
	v_mfma_f32_16x16x32_bf16 v[70:73], v[250:253], v[234:237], v[70:73]
	ds_read_b128 v[250:253], v227 offset:14336
	s_waitcnt vmcnt(12)
	ds_write_b128 v202, v[174:177]
	ds_read_b128 v[170:173], v228 offset:36864
	s_waitcnt lgkmcnt(10)
	v_mfma_f32_16x16x32_bf16 v[74:77], v[238:241], v[212:215], v[74:77]
	v_mfma_f32_16x16x32_bf16 v[78:81], v[238:241], v[216:219], v[78:81]
	v_mfma_f32_16x16x32_bf16 v[82:85], v[238:241], v[220:223], v[82:85]
	v_mfma_f32_16x16x32_bf16 v[114:117], v[238:241], v[234:237], v[114:117]
	ds_read_b128 v[238:241], v229
	s_waitcnt vmcnt(11)
	ds_write_b128 v203, v[178:181]
	ds_read_b128 v[174:177], v228 offset:38912
	s_waitcnt lgkmcnt(11)
	v_mfma_f32_16x16x32_bf16 v[118:121], v[242:245], v[212:215], v[118:121]
	v_mfma_f32_16x16x32_bf16 v[122:125], v[242:245], v[216:219], v[122:125]
	v_mfma_f32_16x16x32_bf16 v[126:129], v[242:245], v[220:223], v[126:129]
	v_mfma_f32_16x16x32_bf16 v[130:133], v[242:245], v[234:237], v[130:133]
	ds_read_b128 v[242:245], v229 offset:2048
	s_waitcnt vmcnt(10)
	ds_write_b128 v204, v[182:185]
	s_waitcnt lgkmcnt(10)
	v_mfma_f32_16x16x32_bf16 v[134:137], v[246:249], v[212:215], v[134:137]
	v_mfma_f32_16x16x32_bf16 v[138:141], v[246:249], v[216:219], v[138:141]
	v_mfma_f32_16x16x32_bf16 v[142:145], v[246:249], v[220:223], v[142:145]
	v_mfma_f32_16x16x32_bf16 v[146:149], v[246:249], v[234:237], v[146:149]
	ds_read_b128 v[246:249], v229 offset:4096
	s_waitcnt vmcnt(9)
	ds_write_b128 v205, v[186:189]
	s_waitcnt lgkmcnt(9)
	v_mfma_f32_16x16x32_bf16 v[150:153], v[250:253], v[212:215], v[150:153]
	v_mfma_f32_16x16x32_bf16 v[154:157], v[250:253], v[216:219], v[154:157]
	v_mfma_f32_16x16x32_bf16 v[158:161], v[250:253], v[220:223], v[158:161]
	v_mfma_f32_16x16x32_bf16 v[2:5], v[250:253], v[234:237], v[2:5]
	ds_read_b128 v[250:253], v229 offset:6144
	s_waitcnt vmcnt(8)
	ds_write_b128 v206, v[190:193]
	s_waitcnt lgkmcnt(6)
	v_mfma_f32_16x16x32_bf16 v[6:9], v[238:241], v[162:165], v[6:9]
	v_mfma_f32_16x16x32_bf16 v[10:13], v[238:241], v[166:169], v[10:13]
	v_mfma_f32_16x16x32_bf16 v[14:17], v[238:241], v[170:173], v[14:17]
	v_mfma_f32_16x16x32_bf16 v[22:25], v[238:241], v[174:177], v[22:25]
	ds_read_b128 v[238:241], v229 offset:8192
	s_waitcnt lgkmcnt(6)
	v_mfma_f32_16x16x32_bf16 v[26:29], v[242:245], v[162:165], v[26:29]
	v_mfma_f32_16x16x32_bf16 v[30:33], v[242:245], v[166:169], v[30:33]
	v_mfma_f32_16x16x32_bf16 v[34:37], v[242:245], v[170:173], v[34:37]
	v_mfma_f32_16x16x32_bf16 v[38:41], v[242:245], v[174:177], v[38:41]
	ds_read_b128 v[242:245], v229 offset:10240
	s_waitcnt lgkmcnt(5)
	v_mfma_f32_16x16x32_bf16 v[42:45], v[246:249], v[162:165], v[42:45]
	v_mfma_f32_16x16x32_bf16 v[46:49], v[246:249], v[166:169], v[46:49]
	v_mfma_f32_16x16x32_bf16 v[50:53], v[246:249], v[170:173], v[50:53]
	v_mfma_f32_16x16x32_bf16 v[54:57], v[246:249], v[174:177], v[54:57]
	ds_read_b128 v[246:249], v229 offset:12288
	s_waitcnt lgkmcnt(4)
	v_mfma_f32_16x16x32_bf16 v[58:61], v[250:253], v[162:165], v[58:61]
	v_mfma_f32_16x16x32_bf16 v[62:65], v[250:253], v[166:169], v[62:65]
	v_mfma_f32_16x16x32_bf16 v[66:69], v[250:253], v[170:173], v[66:69]
	v_mfma_f32_16x16x32_bf16 v[70:73], v[250:253], v[174:177], v[70:73]
	ds_read_b128 v[250:253], v229 offset:14336
	s_waitcnt lgkmcnt(3)
	v_mfma_f32_16x16x32_bf16 v[74:77], v[238:241], v[162:165], v[74:77]
	v_mfma_f32_16x16x32_bf16 v[78:81], v[238:241], v[166:169], v[78:81]
	v_mfma_f32_16x16x32_bf16 v[82:85], v[238:241], v[170:173], v[82:85]
	v_mfma_f32_16x16x32_bf16 v[114:117], v[238:241], v[174:177], v[114:117]
	s_waitcnt lgkmcnt(2)
	v_mfma_f32_16x16x32_bf16 v[118:121], v[242:245], v[162:165], v[118:121]
	v_mfma_f32_16x16x32_bf16 v[122:125], v[242:245], v[166:169], v[122:125]
	v_mfma_f32_16x16x32_bf16 v[126:129], v[242:245], v[170:173], v[126:129]
	v_mfma_f32_16x16x32_bf16 v[130:133], v[242:245], v[174:177], v[130:133]
	s_waitcnt lgkmcnt(0)
	s_addk_i32 s62, 0x80
	s_add_u32 s54, s54, 0x100
	s_addc_u32 s55, s55, 0
	s_add_u32 s52, s52, 0x100
	s_addc_u32 s53, s53, 0
	s_cmp_gt_u32 s64, 12
	s_mov_b32 s64, s63
	s_cbranch_scc1 .Lgemm_out_exit
	s_barrier
	ds_read_b128 v[212:215], v230
	ds_read_b128 v[216:219], v230 offset:2048
	ds_read_b128 v[220:223], v230 offset:4096
	ds_read_b128 v[234:237], v230 offset:6144
	ds_read_b128 v[238:241], v231
	ds_read_b128 v[242:245], v231 offset:2048
	v_mfma_f32_16x16x32_bf16 v[134:137], v[246:249], v[162:165], v[134:137]
	v_mfma_f32_16x16x32_bf16 v[138:141], v[246:249], v[166:169], v[138:141]
	v_mfma_f32_16x16x32_bf16 v[142:145], v[246:249], v[170:173], v[142:145]
	v_mfma_f32_16x16x32_bf16 v[146:149], v[246:249], v[174:177], v[146:149]
	ds_read_b128 v[246:249], v231 offset:4096
	v_mfma_f32_16x16x32_bf16 v[150:153], v[250:253], v[162:165], v[150:153]
	v_mfma_f32_16x16x32_bf16 v[154:157], v[250:253], v[166:169], v[154:157]
	v_mfma_f32_16x16x32_bf16 v[158:161], v[250:253], v[170:173], v[158:161]
	v_mfma_f32_16x16x32_bf16 v[2:5], v[250:253], v[174:177], v[2:5]
	ds_read_b128 v[250:253], v231 offset:6144
	global_load_dwordx4 v[162:165], v196, s[54:55] offset:384
	global_load_dwordx4 v[166:169], v208, s[54:55] offset:384
	global_load_dwordx4 v[170:173], v209, s[54:55] offset:384
	global_load_dwordx4 v[174:177], v210, s[54:55] offset:384
	global_load_dwordx4 v[178:181], v196, s[52:53] offset:384
	global_load_dwordx4 v[182:185], v208, s[52:53] offset:384
	global_load_dwordx4 v[186:189], v209, s[52:53] offset:384
	global_load_dwordx4 v[190:193], v210, s[52:53] offset:384
	s_branch .LBB0_70
; #define GCOMPUTE(AS, BS) GCOMPUTE_KS(AS, BS, 0) GCOMPUTE_KS(AS, BS, 1)
; template <int EPI>
; DI void gemm_phase(const P& p, int l, const u16* __restrict__ A, const u16* __restrict__ Bt, int mpx, char* lds) {
;     ...
;     GCOMPUTE(As0, Bs0)
;     __builtin_amdgcn_sched_barrier(0);
;   }
;   __syncthreads();
;   __builtin_amdgcn_sched_barrier(0);
;   GCOMPUTE(As1, Bs1)
;   __builtin_amdgcn_sched_barrier(0);
.Lgemm_out_exit:
	v_mfma_f32_16x16x32_bf16 v[134:137], v[246:249], v[162:165], v[134:137]
	v_mfma_f32_16x16x32_bf16 v[138:141], v[246:249], v[166:169], v[138:141]
	v_mfma_f32_16x16x32_bf16 v[142:145], v[246:249], v[170:173], v[142:145]
	v_mfma_f32_16x16x32_bf16 v[146:149], v[246:249], v[174:177], v[146:149]
	v_mfma_f32_16x16x32_bf16 v[150:153], v[250:253], v[162:165], v[150:153]
	v_mfma_f32_16x16x32_bf16 v[154:157], v[250:253], v[166:169], v[154:157]
	v_mfma_f32_16x16x32_bf16 v[158:161], v[250:253], v[170:173], v[158:161]
	v_mfma_f32_16x16x32_bf16 v[2:5], v[250:253], v[174:177], v[2:5]
	s_barrier
	ds_read_b128 v[162:165], v231
	ds_read_b128 v[166:169], v230
	ds_read_b128 v[170:173], v230 offset:2048
	ds_read_b128 v[174:177], v230 offset:4096
	ds_read_b128 v[178:181], v230 offset:6144
	s_waitcnt lgkmcnt(3)
	v_mfma_f32_16x16x32_bf16 v[6:9], v[162:165], v[166:169], v[6:9]
	s_waitcnt lgkmcnt(2)
	v_mfma_f32_16x16x32_bf16 v[10:13], v[162:165], v[170:173], v[10:13]
	s_waitcnt lgkmcnt(1)
	v_mfma_f32_16x16x32_bf16 v[14:17], v[162:165], v[174:177], v[14:17]
	s_waitcnt lgkmcnt(0)
	v_mfma_f32_16x16x32_bf16 v[22:25], v[162:165], v[178:181], v[22:25]
	ds_read_b128 v[162:165], v231 offset:2048
	s_waitcnt lgkmcnt(0)
	v_mfma_f32_16x16x32_bf16 v[26:29], v[162:165], v[166:169], v[26:29]
	v_mfma_f32_16x16x32_bf16 v[30:33], v[162:165], v[170:173], v[30:33]
	v_mfma_f32_16x16x32_bf16 v[34:37], v[162:165], v[174:177], v[34:37]
	v_mfma_f32_16x16x32_bf16 v[38:41], v[162:165], v[178:181], v[38:41]
	ds_read_b128 v[162:165], v231 offset:4096
	s_waitcnt lgkmcnt(0)
	v_mfma_f32_16x16x32_bf16 v[42:45], v[162:165], v[166:169], v[42:45]
	v_mfma_f32_16x16x32_bf16 v[46:49], v[162:165], v[170:173], v[46:49]
	v_mfma_f32_16x16x32_bf16 v[50:53], v[162:165], v[174:177], v[50:53]
	v_mfma_f32_16x16x32_bf16 v[54:57], v[162:165], v[178:181], v[54:57]
	ds_read_b128 v[162:165], v231 offset:6144
	s_waitcnt lgkmcnt(0)
	v_mfma_f32_16x16x32_bf16 v[58:61], v[162:165], v[166:169], v[58:61]
	v_mfma_f32_16x16x32_bf16 v[62:65], v[162:165], v[170:173], v[62:65]
	v_mfma_f32_16x16x32_bf16 v[66:69], v[162:165], v[174:177], v[66:69]
	v_mfma_f32_16x16x32_bf16 v[162:165], v[162:165], v[178:181], v[70:73]
	s_nop 2
	ds_read_b128 v[70:73], v231 offset:8192
	s_waitcnt lgkmcnt(0)
	v_mfma_f32_16x16x32_bf16 v[182:185], v[70:73], v[166:169], v[74:77]
	s_nop 2
	ds_read_b128 v[74:77], v233
	v_mfma_f32_16x16x32_bf16 v[186:189], v[70:73], v[170:173], v[78:81]
	v_mfma_f32_16x16x32_bf16 v[190:193], v[70:73], v[174:177], v[82:85]
	v_mfma_f32_16x16x32_bf16 v[212:215], v[70:73], v[178:181], v[114:117]
	ds_read_b128 v[70:73], v231 offset:10240
	s_waitcnt lgkmcnt(0)
	v_mfma_f32_16x16x32_bf16 v[216:219], v[70:73], v[166:169], v[118:121]
	v_mfma_f32_16x16x32_bf16 v[220:223], v[70:73], v[170:173], v[122:125]
	v_mfma_f32_16x16x32_bf16 v[234:237], v[70:73], v[174:177], v[126:129]
	v_mfma_f32_16x16x32_bf16 v[238:241], v[70:73], v[178:181], v[130:133]
	ds_read_b128 v[70:73], v231 offset:12288
	s_waitcnt lgkmcnt(0)
	v_mfma_f32_16x16x32_bf16 v[242:245], v[70:73], v[166:169], v[134:137]
	v_mfma_f32_16x16x32_bf16 v[246:249], v[70:73], v[170:173], v[138:141]
	v_mfma_f32_16x16x32_bf16 v[250:253], v[70:73], v[174:177], v[142:145]
	v_mfma_f32_16x16x32_bf16 v[208:211], v[70:73], v[178:181], v[146:149]
	ds_read_b128 v[70:73], v231 offset:14336
	s_waitcnt lgkmcnt(0)
	v_mfma_f32_16x16x32_bf16 v[178:181], v[70:73], v[178:181], v[2:5]
	s_nop 2
	ds_read_b128 v[2:5], v232
	s_waitcnt lgkmcnt(0)
	v_mfma_f32_16x16x32_bf16 v[146:149], v[74:77], v[2:5], v[6:9]
	s_nop 2
	ds_read_b128 v[6:9], v232 offset:2048
	v_mfma_f32_16x16x32_bf16 v[170:173], v[70:73], v[170:173], v[154:157]
	s_waitcnt lgkmcnt(0)
	v_mfma_f32_16x16x32_bf16 v[154:157], v[74:77], v[6:9], v[10:13]
	s_nop 2
	ds_read_b128 v[10:13], v232 offset:4096
	v_mfma_f32_16x16x32_bf16 v[166:169], v[70:73], v[166:169], v[150:153]
	s_waitcnt lgkmcnt(0)
	v_mfma_f32_16x16x32_bf16 v[150:153], v[74:77], v[10:13], v[14:17]
	s_nop 2
	ds_read_b128 v[14:17], v232 offset:6144
	v_mfma_f32_16x16x32_bf16 v[174:177], v[70:73], v[174:177], v[158:161]
	s_waitcnt lgkmcnt(0)
	v_mfma_f32_16x16x32_bf16 v[158:161], v[74:77], v[14:17], v[22:25]
	s_nop 2
	ds_read_b128 v[22:25], v233 offset:2048
	s_waitcnt lgkmcnt(0)
	v_mfma_f32_16x16x32_bf16 v[138:141], v[22:25], v[2:5], v[26:29]
	s_nop 2
	ds_read_b128 v[26:29], v233 offset:12288
	v_mfma_f32_16x16x32_bf16 v[142:145], v[22:25], v[6:9], v[30:33]
	v_mfma_f32_16x16x32_bf16 v[130:133], v[22:25], v[10:13], v[34:37]
	v_mfma_f32_16x16x32_bf16 v[134:137], v[22:25], v[14:17], v[38:41]
	ds_read_b128 v[22:25], v233 offset:4096
	s_waitcnt lgkmcnt(0)
	v_mfma_f32_16x16x32_bf16 v[122:125], v[22:25], v[2:5], v[42:45]
	v_mfma_f32_16x16x32_bf16 v[126:129], v[22:25], v[6:9], v[46:49]
	v_mfma_f32_16x16x32_bf16 v[114:117], v[22:25], v[10:13], v[50:53]
	v_mfma_f32_16x16x32_bf16 v[118:121], v[22:25], v[14:17], v[54:57]
	ds_read_b128 v[22:25], v233 offset:6144
	s_waitcnt lgkmcnt(0)
	v_mfma_f32_16x16x32_bf16 v[78:81], v[22:25], v[2:5], v[58:61]
	v_mfma_f32_16x16x32_bf16 v[82:85], v[22:25], v[6:9], v[62:65]
	v_mfma_f32_16x16x32_bf16 v[70:73], v[22:25], v[10:13], v[66:69]
	v_mfma_f32_16x16x32_bf16 v[74:77], v[22:25], v[14:17], v[162:165]
	ds_read_b128 v[22:25], v233 offset:8192
	s_nop 1
	ds_read_b128 v[162:165], v233 offset:14336
	s_waitcnt lgkmcnt(1)
	v_mfma_f32_16x16x32_bf16 v[62:65], v[22:25], v[2:5], v[182:185]
	v_mfma_f32_16x16x32_bf16 v[66:69], v[22:25], v[6:9], v[186:189]
	v_mfma_f32_16x16x32_bf16 v[54:57], v[22:25], v[10:13], v[190:193]
	v_mfma_f32_16x16x32_bf16 v[58:61], v[22:25], v[14:17], v[212:215]
	ds_read_b128 v[22:25], v233 offset:10240
	s_waitcnt lgkmcnt(0)
	v_mfma_f32_16x16x32_bf16 v[46:49], v[22:25], v[2:5], v[216:219]
	v_mfma_f32_16x16x32_bf16 v[50:53], v[22:25], v[6:9], v[220:223]
	v_mfma_f32_16x16x32_bf16 v[38:41], v[22:25], v[10:13], v[234:237]
	v_mfma_f32_16x16x32_bf16 v[42:45], v[22:25], v[14:17], v[238:241]
	v_mfma_f32_16x16x32_bf16 v[30:33], v[26:29], v[2:5], v[242:245]
	v_mfma_f32_16x16x32_bf16 v[34:37], v[26:29], v[6:9], v[246:249]
	v_mfma_f32_16x16x32_bf16 v[22:25], v[26:29], v[10:13], v[250:253]
	v_mfma_f32_16x16x32_bf16 v[26:29], v[26:29], v[14:17], v[208:211]
	v_mfma_f32_16x16x32_bf16 v[166:169], v[162:165], v[2:5], v[166:169]
	v_mfma_f32_16x16x32_bf16 v[170:173], v[162:165], v[6:9], v[170:173]
	v_mfma_f32_16x16x32_bf16 v[2:5], v[162:165], v[10:13], v[174:177]
	v_mfma_f32_16x16x32_bf16 v[6:9], v[162:165], v[14:17], v[178:181]
	v_mov_b32_e32 v14, v195
	s_barrier
; DI int tidx() { int t = threadIdx.x; asm volatile("" : "+v"(t)); return t; }
; template <int EPI>
; DI void gemm_phase(const P& p, int l, const u16* __restrict__ A, const u16* __restrict__ Bt, int mpx, char* lds) {
;     ...
;   __syncthreads();
;   GSTORE(As0, Bs0)
;   const int tid_e = tidx();
;   const int lane = tid_e & 63, w = tid_e >> 6, r = lane & 15, g = lane >> 4, wm = w >> 2, wn = w & 3;
;   if constexpr (EPI == 1) {
;     const float alpha = 1.4142135623730951f;
;     float* Cw = (float*)(lds + 65536) + w * (16 * 68);
;     const int mr = m0 < MLAT ? (m0 >> 11) : 16;
;     const int colw = n0 + wn * 64;
;     const float* gate = p.mod + (size_t)(l * 17 + mr) * 3072 + 2048 + colw;
;     const float* xr = ((l == 0) ? (m0 < MLAT ? p.x + (size_t)m0 * 1024 : p.ctx + (size_t)(m0 - MLAT) * 1024)
;                                 : p.out + (size_t)m0 * 1024) + (size_t)(wm * 128) * 1024 + colw;
;     float* Z = (float*)p.slab + (size_t)(m0 + wm * 128) * 1024 + colw;
;     const int c4 = (lane & 15) * 4, rr0 = lane >> 4;
;     const float4 gt = *(const float4*)(gate + c4);
;     float4 xn[4];
; #pragma unroll
;     for (int i = 0; i < 4; ++i) xn[i] = *(const float4*)(xr + (size_t)(rr0 + 4 * i) * 1024 + c4);
; #pragma unroll
;     for (int mi = 0; mi < 8; ++mi) {
;       float4 xv[4];
; #pragma unroll
;       for (int i = 0; i < 4; ++i) xv[i] = xn[i];
;       if (mi < 7) {
; #pragma unroll
;         for (int i = 0; i < 4; ++i) xn[i] = *(const float4*)(xr + (size_t)((mi + 1) * 16 + rr0 + 4 * i) * 1024 + c4);
;       }
; #pragma unroll
;       for (int ni = 0; ni < 4; ++ni)
; #pragma unroll
;         for (int j = 0; j < 4; ++j) Cw[(g * 4 + j) * 68 + ni * 16 + r] = acc[mi][ni][j];
;       __builtin_amdgcn_fence(__ATOMIC_RELEASE, "wavefront");
; #pragma unroll
;       for (int i = 0; i < 4; ++i) {
;         const int row = rr0 + 4 * i;
;         const float4 a = *(const float4*)&Cw[row * 68 + c4];
	s_waitcnt vmcnt(7)
	ds_write_b128 v198, v[18:21]
	s_waitcnt vmcnt(5)
	ds_write_b128 v198, v[86:89] offset:8192
	s_waitcnt vmcnt(4)
	ds_write_b128 v198, v[90:93] offset:16384
	s_waitcnt vmcnt(3)
	ds_write_b128 v198, v[94:97] offset:24576
	ds_write_b128 v198, v[98:101] offset:32768
	s_waitcnt vmcnt(2)
	ds_write_b128 v198, v[102:105] offset:40960
	s_waitcnt vmcnt(1)
	ds_write_b128 v198, v[106:109] offset:49152
	s_waitcnt vmcnt(0)
	ds_write_b128 v198, v[110:113] offset:57344
	s_movk_i32 s2, 0x1100
	v_lshrrev_b32_e32 v0, 6, v14
	v_mul_lo_u32 v19, v0, s2
	s_min_i32 s2, s60, 0x8000
	s_lshr_b32 s2, s2, 11
	s_mul_i32 s46, s50, 17
	v_and_b32_e32 v0, 0xc0, v14
	s_add_i32 s2, s2, s46
	v_readlane_b32 s64, v255, 28
	v_or_b32_e32 v0, s61, v0
	s_mul_hi_i32 s47, s2, 0x3000
	s_mulk_i32 s2, 0x3000
	v_readlane_b32 s66, v255, 30
	v_readlane_b32 s67, v255, 31
	s_add_u32 s46, s66, s2
	v_lshlrev_b64 v[10:11], 2, v[0:1]
	v_mov_b32_e32 v0, 0x8000
	s_addc_u32 s47, s67, s47
	v_sub_co_u32_e32 v0, vcc, s60, v0
	v_lshl_add_u64 v[12:13], s[46:47], 0, v[10:11]
	s_and_b64 s[46:47], vcc, exec
	v_readfirstlane_b32 s2, v0
	s_cselect_b32 s2, s60, s2
	s_cselect_b32 s48, 0, 16
	s_and_b64 s[46:47], s[0:1], exec
	s_cselect_b32 s46, s48, 0x88
	s_cselect_b32 s2, s2, s60
	s_add_u32 s46, s96, s46
	s_addc_u32 s47, s97, 0
	s_load_dwordx2 s[46:47], s[46:47], 0x0
	v_ashrrev_i32_e32 v0, 1, v14
	v_and_b32_e32 v18, 15, v14
	v_bfe_u32 v88, v14, 4, 2
	s_lshl_b64 s[48:49], s[2:3], 12
	v_and_b32_e32 v14, 0xffffff80, v0
	s_waitcnt lgkmcnt(0)
	s_add_u32 s46, s46, s48
	v_ashrrev_i32_e32 v15, 31, v14
	s_addc_u32 s47, s47, s49
	v_lshlrev_b64 v[16:17], 12, v[14:15]
	v_lshl_add_u64 v[16:17], s[46:47], 0, v[16:17]
	v_add_u32_e32 v14, s60, v14
	v_lshl_add_u64 v[16:17], v[16:17], 0, v[10:11]
	v_ashrrev_i32_e32 v15, 31, v14
	v_lshlrev_b32_e32 v0, 4, v18
	v_lshlrev_b64 v[14:15], 12, v[14:15]
	v_lshlrev_b32_e32 v20, 2, v18
	v_lshl_add_u64 v[16:17], v[16:17], 0, v[0:1]
	v_lshlrev_b32_e32 v86, 12, v88
	v_mov_b32_e32 v87, v1
	v_lshl_add_u64 v[14:15], s[18:19], 0, v[14:15]
	v_lshl_add_u64 v[162:163], v[16:17], 0, v[86:87]
	v_add3_u32 v16, s78, v19, v20
	s_movk_i32 s2, 0x440
	v_lshl_add_u64 v[12:13], v[12:13], 0, v[0:1]
	v_lshl_add_u64 v[10:11], v[14:15], 0, v[10:11]
	v_mad_u32_u24 v165, v88, s2, v16
	s_movk_i32 s2, 0x2000
	v_lshl_add_u64 v[14:15], v[10:11], 0, v[0:1]
	v_add_co_u32_e32 v10, vcc, s2, v12
	ds_write2_b32 v165, v146, v154 offset1:16
	ds_write2_b32 v165, v147, v155 offset0:68 offset1:84
	ds_write2_b32 v165, v148, v156 offset0:136 offset1:152
	ds_write2_b32 v165, v149, v157 offset0:204 offset1:220
	ds_write2_b32 v165, v150, v158 offset0:32 offset1:48
	ds_write2_b32 v165, v151, v159 offset0:100 offset1:116
	ds_write2_b32 v165, v152, v160 offset0:168 offset1:184
	ds_write2_b32 v165, v153, v161 offset0:236 offset1:252
	v_addc_co_u32_e32 v11, vcc, 0, v13, vcc
	v_mad_u32_u24 v17, v18, 12, v16
	global_load_dwordx4 v[18:21], v[10:11], off
	s_nop 0
	global_load_dwordx4 v[10:13], v[162:163], off
	v_or_b32_e32 v0, 4, v88
	v_add_co_u32_e32 v16, vcc, s94, v162
	v_mad_u32_u24 v164, v88, s79, v17
	v_mad_u32_u24 v158, v0, s79, v17
	v_addc_co_u32_e32 v17, vcc, 0, v163, vcc
	global_load_dwordx4 v[102:105], v[16:17], off
	v_add_co_u32_e32 v16, vcc, s21, v162
	v_lshlrev_b32_e32 v0, 12, v0
	s_nop 0
	v_addc_co_u32_e32 v17, vcc, 0, v163, vcc
	global_load_dwordx4 v[94:97], v[16:17], off
	v_lshl_add_u64 v[156:157], v[14:15], 0, v[0:1]
	v_or_b32_e32 v0, 0x8000, v86
	v_lshl_add_u64 v[154:155], v[14:15], 0, v[0:1]
	v_or_b32_e32 v0, 0xc000, v86
	s_mov_b32 s2, 0xc000
	v_lshl_add_u64 v[152:153], v[14:15], 0, v[86:87]
	v_lshl_add_u64 v[150:151], v[14:15], 0, v[0:1]
	v_add_co_u32_e32 v14, vcc, s2, v162
	s_mov_b32 s2, 0x14000
	s_nop 0
	v_addc_co_u32_e32 v15, vcc, 0, v163, vcc
	global_load_dwordx4 v[86:89], v[14:15], off
	v_add_co_u32_e32 v14, vcc, s85, v162
	s_mov_b32 s46, 0x30000
	s_nop 0
	v_addc_co_u32_e32 v15, vcc, 0, v163, vcc
	global_load_dwordx4 v[146:149], v[14:15], off
	v_add_co_u32_e32 v14, vcc, s2, v162
	s_mov_b32 s2, 0x18000
	s_nop 0
	v_addc_co_u32_e32 v15, vcc, 0, v163, vcc
	global_load_dwordx4 v[106:109], v[14:15], off
	v_add_co_u32_e32 v14, vcc, s2, v162
	s_mov_b32 s2, 0x1c000
	s_nop 0
	v_addc_co_u32_e32 v15, vcc, 0, v163, vcc
	global_load_dwordx4 v[98:101], v[14:15], off
	v_add_co_u32_e32 v14, vcc, s2, v162
	s_mov_b32 s2, 0x24000
	s_nop 0
	v_addc_co_u32_e32 v15, vcc, 0, v163, vcc
	global_load_dwordx4 v[90:93], v[14:15], off
	ds_read_b128 v[14:17], v164
	s_mov_b32 s60, s58
	s_mov_b32 s61, s59
	s_mov_b64 s[48:49], s[42:43]
	v_readlane_b32 s65, v255, 29
	v_readlane_b32 s68, v255, 32
	v_readlane_b32 s69, v255, 33
	v_readlane_b32 s70, v255, 34
	v_readlane_b32 s71, v255, 35
	s_waitcnt vmcnt(8) lgkmcnt(0)
	v_pk_mul_f32 v[14:15], v[18:19], v[14:15]
	s_waitcnt vmcnt(7)
	v_pk_fma_f32 v[10:11], v[10:11], s[34:35], v[14:15] op_sel_hi:[1,0,1]
	v_pk_mul_f32 v[14:15], v[20:21], v[16:17]
	s_nop 0
	v_pk_fma_f32 v[12:13], v[12:13], s[34:35], v[14:15] op_sel_hi:[1,0,1]
	global_store_dwordx4 v[152:153], v[10:13], off
	ds_read_b128 v[10:13], v158
	s_waitcnt lgkmcnt(0)
	v_pk_mul_f32 v[10:11], v[18:19], v[10:11]
	v_pk_mul_f32 v[12:13], v[20:21], v[12:13]
	s_waitcnt vmcnt(7)
	v_pk_fma_f32 v[10:11], v[102:103], s[34:35], v[10:11] op_sel_hi:[1,0,1]
	v_pk_fma_f32 v[12:13], v[104:105], s[34:35], v[12:13] op_sel_hi:[1,0,1]
	global_store_dwordx4 v[156:157], v[10:13], off
	ds_read_b128 v[10:13], v158 offset:1088
	s_waitcnt lgkmcnt(0)
	v_pk_mul_f32 v[10:11], v[18:19], v[10:11]
	v_pk_mul_f32 v[12:13], v[20:21], v[12:13]
	s_waitcnt vmcnt(7)
; template <int EPI>
; DI void gemm_phase(const P& p, int l, const u16* __restrict__ A, const u16* __restrict__ Bt, int mpx, char* lds) {
;     ...
;     for (int mi = 0; mi < 8; ++mi) {
;       float4 xv[4];
; #pragma unroll
;       for (int i = 0; i < 4; ++i) xv[i] = xn[i];
;       if (mi < 7) {
; #pragma unroll
;         for (int i = 0; i < 4; ++i) xn[i] = *(const float4*)(xr + (size_t)((mi + 1) * 16 + rr0 + 4 * i) * 1024 + c4);
;       }
; #pragma unroll
;       for (int ni = 0; ni < 4; ++ni)
; #pragma unroll
;         for (int j = 0; j < 4; ++j) Cw[(g * 4 + j) * 68 + ni * 16 + r] = acc[mi][ni][j];
;       __builtin_amdgcn_fence(__ATOMIC_RELEASE, "wavefront");
; #pragma unroll
;       for (int i = 0; i < 4; ++i) {
;         const int row = rr0 + 4 * i;
;         const float4 a = *(const float4*)&Cw[row * 68 + c4];
;         float4 z;
;         z.x = alpha * xv[i].x + gt.x * a.x;
;         z.y = alpha * xv[i].y + gt.y * a.y;
;         z.z = alpha * xv[i].z + gt.z * a.z;
;         z.w = alpha * xv[i].w + gt.w * a.w;
;         *(float4*)(Z + (size_t)(mi * 16 + row) * 1024 + c4) = z;
;       }
	v_pk_fma_f32 v[10:11], v[94:95], s[34:35], v[10:11] op_sel_hi:[1,0,1]
	v_pk_fma_f32 v[12:13], v[96:97], s[34:35], v[12:13] op_sel_hi:[1,0,1]
	global_store_dwordx4 v[154:155], v[10:13], off
	ds_read_b128 v[10:13], v158 offset:2176
	s_waitcnt lgkmcnt(0)
	v_pk_mul_f32 v[10:11], v[18:19], v[10:11]
	v_pk_mul_f32 v[12:13], v[20:21], v[12:13]
	s_waitcnt vmcnt(7)
	v_pk_fma_f32 v[10:11], v[86:87], s[34:35], v[10:11] op_sel_hi:[1,0,1]
	v_pk_fma_f32 v[12:13], v[88:89], s[34:35], v[12:13] op_sel_hi:[1,0,1]
	global_store_dwordx4 v[150:151], v[10:13], off
	ds_write2_b32 v165, v138, v142 offset1:16
	ds_write2_b32 v165, v139, v143 offset0:68 offset1:84
	ds_write2_b32 v165, v140, v144 offset0:136 offset1:152
	ds_write2_b32 v165, v141, v145 offset0:204 offset1:220
	ds_write2_b32 v165, v130, v134 offset0:32 offset1:48
	ds_write2_b32 v165, v131, v135 offset0:100 offset1:116
	ds_write2_b32 v165, v132, v136 offset0:168 offset1:184
	ds_write2_b32 v165, v133, v137 offset0:236 offset1:252
	v_add_co_u32_e32 v10, vcc, s33, v162
	s_nop 1
	v_addc_co_u32_e32 v11, vcc, 0, v163, vcc
	global_load_dwordx4 v[110:113], v[10:11], off
	v_add_co_u32_e32 v10, vcc, s2, v162
	s_mov_b32 s2, 0x28000
	s_nop 0
	v_addc_co_u32_e32 v11, vcc, 0, v163, vcc
	global_load_dwordx4 v[102:105], v[10:11], off
	v_add_co_u32_e32 v10, vcc, s2, v162
	s_mov_b32 s2, 0x2c000
	s_nop 0
	v_addc_co_u32_e32 v11, vcc, 0, v163, vcc
	global_load_dwordx4 v[94:97], v[10:11], off
	v_add_co_u32_e32 v10, vcc, s2, v162
	s_mov_b32 s2, 0x34000
	s_nop 0
	v_addc_co_u32_e32 v11, vcc, 0, v163, vcc
	global_load_dwordx4 v[86:89], v[10:11], off
	ds_read_b128 v[10:13], v164
	v_add_co_u32_e32 v14, vcc, s85, v152
	s_waitcnt lgkmcnt(0)
	v_pk_mul_f32 v[10:11], v[18:19], v[10:11]
	v_pk_mul_f32 v[12:13], v[20:21], v[12:13]
	s_waitcnt vmcnt(11)
	v_pk_fma_f32 v[10:11], v[146:147], s[34:35], v[10:11] op_sel_hi:[1,0,1]
	v_pk_fma_f32 v[12:13], v[148:149], s[34:35], v[12:13] op_sel_hi:[1,0,1]
	v_addc_co_u32_e32 v15, vcc, 0, v153, vcc
	global_store_dwordx4 v[14:15], v[10:13], off
	ds_read_b128 v[10:13], v158
	v_add_co_u32_e32 v14, vcc, s85, v156
	s_waitcnt lgkmcnt(0)
	v_pk_mul_f32 v[10:11], v[18:19], v[10:11]
	v_pk_mul_f32 v[12:13], v[20:21], v[12:13]
	s_waitcnt vmcnt(11)
	v_pk_fma_f32 v[10:11], v[106:107], s[34:35], v[10:11] op_sel_hi:[1,0,1]
	v_pk_fma_f32 v[12:13], v[108:109], s[34:35], v[12:13] op_sel_hi:[1,0,1]
	v_addc_co_u32_e32 v15, vcc, 0, v157, vcc
	global_store_dwordx4 v[14:15], v[10:13], off
	ds_read_b128 v[10:13], v158 offset:1088
	v_add_co_u32_e32 v14, vcc, s85, v154
	s_waitcnt lgkmcnt(0)
	v_pk_mul_f32 v[10:11], v[18:19], v[10:11]
	v_pk_mul_f32 v[12:13], v[20:21], v[12:13]
	s_waitcnt vmcnt(11)
	v_pk_fma_f32 v[10:11], v[98:99], s[34:35], v[10:11] op_sel_hi:[1,0,1]
	v_pk_fma_f32 v[12:13], v[100:101], s[34:35], v[12:13] op_sel_hi:[1,0,1]
	v_addc_co_u32_e32 v15, vcc, 0, v155, vcc
	global_store_dwordx4 v[14:15], v[10:13], off
	ds_read_b128 v[10:13], v158 offset:2176
	v_add_co_u32_e32 v14, vcc, s85, v150
	s_waitcnt lgkmcnt(0)
	v_pk_mul_f32 v[10:11], v[18:19], v[10:11]
	v_pk_mul_f32 v[12:13], v[20:21], v[12:13]
	s_waitcnt vmcnt(11)
	v_pk_fma_f32 v[10:11], v[90:91], s[34:35], v[10:11] op_sel_hi:[1,0,1]
	v_pk_fma_f32 v[12:13], v[92:93], s[34:35], v[12:13] op_sel_hi:[1,0,1]
	v_addc_co_u32_e32 v15, vcc, 0, v151, vcc
	global_store_dwordx4 v[14:15], v[10:13], off
	ds_write2_b32 v165, v122, v126 offset1:16
	ds_write2_b32 v165, v123, v127 offset0:68 offset1:84
	ds_write2_b32 v165, v124, v128 offset0:136 offset1:152
	ds_write2_b32 v165, v125, v129 offset0:204 offset1:220
	ds_write2_b32 v165, v114, v118 offset0:32 offset1:48
	ds_write2_b32 v165, v115, v119 offset0:100 offset1:116
	ds_write2_b32 v165, v116, v120 offset0:168 offset1:184
	ds_write2_b32 v165, v117, v121 offset0:236 offset1:252
	v_add_co_u32_e32 v10, vcc, s46, v162
	s_nop 1
	v_addc_co_u32_e32 v11, vcc, 0, v163, vcc
	global_load_dwordx4 v[114:117], v[10:11], off
	v_add_co_u32_e32 v10, vcc, s2, v162
	s_mov_b32 s2, 0x38000
	s_nop 0
	v_addc_co_u32_e32 v11, vcc, 0, v163, vcc
	global_load_dwordx4 v[106:109], v[10:11], off
	v_add_co_u32_e32 v10, vcc, s2, v162
	s_mov_b32 s2, 0x3c000
	s_nop 0
	v_addc_co_u32_e32 v11, vcc, 0, v163, vcc
	global_load_dwordx4 v[98:101], v[10:11], off
	v_add_co_u32_e32 v10, vcc, s2, v162
	s_mov_b32 s2, 0x44000
	s_nop 0
	v_addc_co_u32_e32 v11, vcc, 0, v163, vcc
	global_load_dwordx4 v[90:93], v[10:11], off
	ds_read_b128 v[10:13], v164
	v_add_co_u32_e32 v14, vcc, s33, v152
	s_waitcnt lgkmcnt(0)
	v_pk_mul_f32 v[10:11], v[18:19], v[10:11]
	v_pk_mul_f32 v[12:13], v[20:21], v[12:13]
	s_waitcnt vmcnt(11)
	v_pk_fma_f32 v[10:11], v[110:111], s[34:35], v[10:11] op_sel_hi:[1,0,1]
	v_pk_fma_f32 v[12:13], v[112:113], s[34:35], v[12:13] op_sel_hi:[1,0,1]
	v_addc_co_u32_e32 v15, vcc, 0, v153, vcc
	global_store_dwordx4 v[14:15], v[10:13], off
	ds_read_b128 v[10:13], v158
	v_add_co_u32_e32 v14, vcc, s33, v156
	s_waitcnt lgkmcnt(0)
	v_pk_mul_f32 v[10:11], v[18:19], v[10:11]
	v_pk_mul_f32 v[12:13], v[20:21], v[12:13]
	s_waitcnt vmcnt(11)
	v_pk_fma_f32 v[10:11], v[102:103], s[34:35], v[10:11] op_sel_hi:[1,0,1]
	v_pk_fma_f32 v[12:13], v[104:105], s[34:35], v[12:13] op_sel_hi:[1,0,1]
	v_addc_co_u32_e32 v15, vcc, 0, v157, vcc
	global_store_dwordx4 v[14:15], v[10:13], off
	ds_read_b128 v[10:13], v158 offset:1088
	v_add_co_u32_e32 v14, vcc, s33, v154
	s_waitcnt lgkmcnt(0)
	v_pk_mul_f32 v[10:11], v[18:19], v[10:11]
	v_pk_mul_f32 v[12:13], v[20:21], v[12:13]
	s_waitcnt vmcnt(11)
	v_pk_fma_f32 v[10:11], v[94:95], s[34:35], v[10:11] op_sel_hi:[1,0,1]
	v_pk_fma_f32 v[12:13], v[96:97], s[34:35], v[12:13] op_sel_hi:[1,0,1]
	v_addc_co_u32_e32 v15, vcc, 0, v155, vcc
	global_store_dwordx4 v[14:15], v[10:13], off
	ds_read_b128 v[10:13], v158 offset:2176
	v_add_co_u32_e32 v14, vcc, s33, v150
	s_waitcnt lgkmcnt(0)
; template <int EPI>
; DI void gemm_phase(const P& p, int l, const u16* __restrict__ A, const u16* __restrict__ Bt, int mpx, char* lds) {
;     ...
;     for (int mi = 0; mi < 8; ++mi) {
;       float4 xv[4];
; #pragma unroll
;       for (int i = 0; i < 4; ++i) xv[i] = xn[i];
;       if (mi < 7) {
; #pragma unroll
;         for (int i = 0; i < 4; ++i) xn[i] = *(const float4*)(xr + (size_t)((mi + 1) * 16 + rr0 + 4 * i) * 1024 + c4);
;       }
; #pragma unroll
;       for (int ni = 0; ni < 4; ++ni)
; #pragma unroll
;         for (int j = 0; j < 4; ++j) Cw[(g * 4 + j) * 68 + ni * 16 + r] = acc[mi][ni][j];
;       __builtin_amdgcn_fence(__ATOMIC_RELEASE, "wavefront");
; #pragma unroll
;       for (int i = 0; i < 4; ++i) {
;         const int row = rr0 + 4 * i;
;         const float4 a = *(const float4*)&Cw[row * 68 + c4];
;         float4 z;
;         z.x = alpha * xv[i].x + gt.x * a.x;
;         z.y = alpha * xv[i].y + gt.y * a.y;
;         z.z = alpha * xv[i].z + gt.z * a.z;
;         z.w = alpha * xv[i].w + gt.w * a.w;
;         *(float4*)(Z + (size_t)(mi * 16 + row) * 1024 + c4) = z;
;       }
	v_pk_mul_f32 v[10:11], v[18:19], v[10:11]
	v_pk_mul_f32 v[12:13], v[20:21], v[12:13]
	s_waitcnt vmcnt(11)
	v_pk_fma_f32 v[10:11], v[86:87], s[34:35], v[10:11] op_sel_hi:[1,0,1]
	v_pk_fma_f32 v[12:13], v[88:89], s[34:35], v[12:13] op_sel_hi:[1,0,1]
	v_addc_co_u32_e32 v15, vcc, 0, v151, vcc
	global_store_dwordx4 v[14:15], v[10:13], off
	ds_write2_b32 v165, v78, v82 offset1:16
	ds_write2_b32 v165, v79, v83 offset0:68 offset1:84
	ds_write2_b32 v165, v80, v84 offset0:136 offset1:152
	ds_write2_b32 v165, v81, v85 offset0:204 offset1:220
	ds_write2_b32 v165, v70, v74 offset0:32 offset1:48
	ds_write2_b32 v165, v71, v75 offset0:100 offset1:116
	ds_write2_b32 v165, v72, v76 offset0:168 offset1:184
	ds_write2_b32 v165, v73, v77 offset0:236 offset1:252
	v_add_co_u32_e32 v10, vcc, s35, v162
	s_nop 1
	v_addc_co_u32_e32 v11, vcc, 0, v163, vcc
	global_load_dwordx4 v[82:85], v[10:11], off
	v_add_co_u32_e32 v10, vcc, s2, v162
	s_mov_b32 s2, 0x48000
	s_nop 0
	v_addc_co_u32_e32 v11, vcc, 0, v163, vcc
	global_load_dwordx4 v[78:81], v[10:11], off
	v_add_co_u32_e32 v10, vcc, s2, v162
	s_mov_b32 s2, 0x4c000
	s_nop 0
	v_addc_co_u32_e32 v11, vcc, 0, v163, vcc
	global_load_dwordx4 v[74:77], v[10:11], off
	v_add_co_u32_e32 v10, vcc, s2, v162
	s_mov_b32 s2, 0x54000
	s_nop 0
	v_addc_co_u32_e32 v11, vcc, 0, v163, vcc
	global_load_dwordx4 v[70:73], v[10:11], off
	ds_read_b128 v[10:13], v164
	v_add_co_u32_e32 v14, vcc, s46, v152
	s_waitcnt lgkmcnt(0)
	v_pk_mul_f32 v[10:11], v[18:19], v[10:11]
	v_pk_mul_f32 v[12:13], v[20:21], v[12:13]
	s_waitcnt vmcnt(11)
	v_pk_fma_f32 v[10:11], v[114:115], s[34:35], v[10:11] op_sel_hi:[1,0,1]
	v_pk_fma_f32 v[12:13], v[116:117], s[34:35], v[12:13] op_sel_hi:[1,0,1]
	v_addc_co_u32_e32 v15, vcc, 0, v153, vcc
	global_store_dwordx4 v[14:15], v[10:13], off
	ds_read_b128 v[10:13], v158
	v_add_co_u32_e32 v14, vcc, s46, v156
	s_waitcnt lgkmcnt(0)
	v_pk_mul_f32 v[10:11], v[18:19], v[10:11]
	v_pk_mul_f32 v[12:13], v[20:21], v[12:13]
	s_waitcnt vmcnt(11)
	v_pk_fma_f32 v[10:11], v[106:107], s[34:35], v[10:11] op_sel_hi:[1,0,1]
	v_pk_fma_f32 v[12:13], v[108:109], s[34:35], v[12:13] op_sel_hi:[1,0,1]
	v_addc_co_u32_e32 v15, vcc, 0, v157, vcc
	global_store_dwordx4 v[14:15], v[10:13], off
	ds_read_b128 v[10:13], v158 offset:1088
	v_add_co_u32_e32 v14, vcc, s46, v154
	s_waitcnt lgkmcnt(0)
	v_pk_mul_f32 v[10:11], v[18:19], v[10:11]
	v_pk_mul_f32 v[12:13], v[20:21], v[12:13]
	s_waitcnt vmcnt(11)
	v_pk_fma_f32 v[10:11], v[98:99], s[34:35], v[10:11] op_sel_hi:[1,0,1]
	v_pk_fma_f32 v[12:13], v[100:101], s[34:35], v[12:13] op_sel_hi:[1,0,1]
	v_addc_co_u32_e32 v15, vcc, 0, v155, vcc
	global_store_dwordx4 v[14:15], v[10:13], off
	ds_read_b128 v[10:13], v158 offset:2176
	v_add_co_u32_e32 v14, vcc, s46, v150
	s_mov_b32 s46, 0x50000
	s_nop 0
	v_addc_co_u32_e32 v15, vcc, 0, v151, vcc
	s_waitcnt lgkmcnt(0)
	v_pk_mul_f32 v[10:11], v[18:19], v[10:11]
	v_pk_mul_f32 v[12:13], v[20:21], v[12:13]
	s_waitcnt vmcnt(11)
	v_pk_fma_f32 v[10:11], v[90:91], s[34:35], v[10:11] op_sel_hi:[1,0,1]
	v_pk_fma_f32 v[12:13], v[92:93], s[34:35], v[12:13] op_sel_hi:[1,0,1]
	global_store_dwordx4 v[14:15], v[10:13], off
	ds_write2_b32 v165, v62, v66 offset1:16
	ds_write2_b32 v165, v63, v67 offset0:68 offset1:84
	ds_write2_b32 v165, v64, v68 offset0:136 offset1:152
	ds_write2_b32 v165, v65, v69 offset0:204 offset1:220
	ds_write2_b32 v165, v54, v58 offset0:32 offset1:48
	ds_write2_b32 v165, v55, v59 offset0:100 offset1:116
	ds_write2_b32 v165, v56, v60 offset0:168 offset1:184
	ds_write2_b32 v165, v57, v61 offset0:236 offset1:252
	v_add_co_u32_e32 v10, vcc, s46, v162
	s_nop 1
	v_addc_co_u32_e32 v11, vcc, 0, v163, vcc
	global_load_dwordx4 v[66:69], v[10:11], off
	v_add_co_u32_e32 v10, vcc, s2, v162
	s_mov_b32 s2, 0x58000
	s_nop 0
	v_addc_co_u32_e32 v11, vcc, 0, v163, vcc
	global_load_dwordx4 v[62:65], v[10:11], off
	v_add_co_u32_e32 v10, vcc, s2, v162
	s_mov_b32 s2, 0x5c000
	s_nop 0
	v_addc_co_u32_e32 v11, vcc, 0, v163, vcc
	global_load_dwordx4 v[58:61], v[10:11], off
	v_add_co_u32_e32 v10, vcc, s2, v162
	s_mov_b32 s2, 0x64000
	s_nop 0
	v_addc_co_u32_e32 v11, vcc, 0, v163, vcc
	global_load_dwordx4 v[54:57], v[10:11], off
	ds_read_b128 v[10:13], v164
	v_add_co_u32_e32 v14, vcc, s35, v152
	s_waitcnt lgkmcnt(0)
	v_pk_mul_f32 v[10:11], v[18:19], v[10:11]
	v_pk_mul_f32 v[12:13], v[20:21], v[12:13]
	s_waitcnt vmcnt(11)
	v_pk_fma_f32 v[10:11], v[82:83], s[34:35], v[10:11] op_sel_hi:[1,0,1]
	v_pk_fma_f32 v[12:13], v[84:85], s[34:35], v[12:13] op_sel_hi:[1,0,1]
	v_addc_co_u32_e32 v15, vcc, 0, v153, vcc
	global_store_dwordx4 v[14:15], v[10:13], off
	ds_read_b128 v[10:13], v158
	v_add_co_u32_e32 v14, vcc, s35, v156
	s_waitcnt lgkmcnt(0)
	v_pk_mul_f32 v[10:11], v[18:19], v[10:11]
	v_pk_mul_f32 v[12:13], v[20:21], v[12:13]
	s_waitcnt vmcnt(11)
	v_pk_fma_f32 v[10:11], v[78:79], s[34:35], v[10:11] op_sel_hi:[1,0,1]
	v_pk_fma_f32 v[12:13], v[80:81], s[34:35], v[12:13] op_sel_hi:[1,0,1]
	v_addc_co_u32_e32 v15, vcc, 0, v157, vcc
	global_store_dwordx4 v[14:15], v[10:13], off
	ds_read_b128 v[10:13], v158 offset:1088
	v_add_co_u32_e32 v14, vcc, s35, v154
	s_waitcnt lgkmcnt(0)
	v_pk_mul_f32 v[10:11], v[18:19], v[10:11]
	v_pk_mul_f32 v[12:13], v[20:21], v[12:13]
	s_waitcnt vmcnt(11)
	v_pk_fma_f32 v[10:11], v[74:75], s[34:35], v[10:11] op_sel_hi:[1,0,1]
	v_pk_fma_f32 v[12:13], v[76:77], s[34:35], v[12:13] op_sel_hi:[1,0,1]
	v_addc_co_u32_e32 v15, vcc, 0, v155, vcc
	global_store_dwordx4 v[14:15], v[10:13], off
	ds_read_b128 v[10:13], v158 offset:2176
	v_add_co_u32_e32 v14, vcc, s35, v150
	s_waitcnt lgkmcnt(0)
	v_pk_mul_f32 v[10:11], v[18:19], v[10:11]
	v_pk_mul_f32 v[12:13], v[20:21], v[12:13]
	s_waitcnt vmcnt(11)
; template <int EPI>
; DI void gemm_phase(const P& p, int l, const u16* __restrict__ A, const u16* __restrict__ Bt, int mpx, char* lds) {
;     ...
;     for (int mi = 0; mi < 8; ++mi) {
;       float4 xv[4];
; #pragma unroll
;       for (int i = 0; i < 4; ++i) xv[i] = xn[i];
;       if (mi < 7) {
; #pragma unroll
;         for (int i = 0; i < 4; ++i) xn[i] = *(const float4*)(xr + (size_t)((mi + 1) * 16 + rr0 + 4 * i) * 1024 + c4);
;       }
; #pragma unroll
;       for (int ni = 0; ni < 4; ++ni)
; #pragma unroll
;         for (int j = 0; j < 4; ++j) Cw[(g * 4 + j) * 68 + ni * 16 + r] = acc[mi][ni][j];
;       __builtin_amdgcn_fence(__ATOMIC_RELEASE, "wavefront");
; #pragma unroll
;       for (int i = 0; i < 4; ++i) {
;         const int row = rr0 + 4 * i;
;         const float4 a = *(const float4*)&Cw[row * 68 + c4];
;         float4 z;
;         z.x = alpha * xv[i].x + gt.x * a.x;
;         z.y = alpha * xv[i].y + gt.y * a.y;
;         z.z = alpha * xv[i].z + gt.z * a.z;
;         z.w = alpha * xv[i].w + gt.w * a.w;
;         *(float4*)(Z + (size_t)(mi * 16 + row) * 1024 + c4) = z;
;       }
	v_pk_fma_f32 v[10:11], v[70:71], s[34:35], v[10:11] op_sel_hi:[1,0,1]
	v_pk_fma_f32 v[12:13], v[72:73], s[34:35], v[12:13] op_sel_hi:[1,0,1]
	v_addc_co_u32_e32 v15, vcc, 0, v151, vcc
	global_store_dwordx4 v[14:15], v[10:13], off
	ds_write2_b32 v165, v46, v50 offset1:16
	ds_write2_b32 v165, v47, v51 offset0:68 offset1:84
	ds_write2_b32 v165, v48, v52 offset0:136 offset1:152
	ds_write2_b32 v165, v49, v53 offset0:204 offset1:220
	ds_write2_b32 v165, v38, v42 offset0:32 offset1:48
	ds_write2_b32 v165, v39, v43 offset0:100 offset1:116
	ds_write2_b32 v165, v40, v44 offset0:168 offset1:184
	ds_write2_b32 v165, v41, v45 offset0:236 offset1:252
	v_add_co_u32_e32 v10, vcc, s39, v162
	s_nop 1
	v_addc_co_u32_e32 v11, vcc, 0, v163, vcc
	global_load_dwordx4 v[50:53], v[10:11], off
	v_add_co_u32_e32 v10, vcc, s2, v162
	s_mov_b32 s2, 0x68000
	s_nop 0
	v_addc_co_u32_e32 v11, vcc, 0, v163, vcc
	global_load_dwordx4 v[46:49], v[10:11], off
	v_add_co_u32_e32 v10, vcc, s2, v162
	s_mov_b32 s2, 0x6c000
	s_nop 0
	v_addc_co_u32_e32 v11, vcc, 0, v163, vcc
	global_load_dwordx4 v[42:45], v[10:11], off
	v_add_co_u32_e32 v10, vcc, s2, v162
	s_mov_b32 s2, 0x74000
	s_nop 0
	v_addc_co_u32_e32 v11, vcc, 0, v163, vcc
	global_load_dwordx4 v[38:41], v[10:11], off
	ds_read_b128 v[10:13], v164
	v_add_co_u32_e32 v14, vcc, s46, v152
	s_waitcnt lgkmcnt(0)
	v_pk_mul_f32 v[10:11], v[18:19], v[10:11]
	v_pk_mul_f32 v[12:13], v[20:21], v[12:13]
	s_waitcnt vmcnt(11)
	v_pk_fma_f32 v[10:11], v[66:67], s[34:35], v[10:11] op_sel_hi:[1,0,1]
	v_pk_fma_f32 v[12:13], v[68:69], s[34:35], v[12:13] op_sel_hi:[1,0,1]
	v_addc_co_u32_e32 v15, vcc, 0, v153, vcc
	global_store_dwordx4 v[14:15], v[10:13], off
	ds_read_b128 v[10:13], v158
	v_add_co_u32_e32 v14, vcc, s46, v156
	s_waitcnt lgkmcnt(0)
	v_pk_mul_f32 v[10:11], v[18:19], v[10:11]
	v_pk_mul_f32 v[12:13], v[20:21], v[12:13]
	s_waitcnt vmcnt(11)
	v_pk_fma_f32 v[10:11], v[62:63], s[34:35], v[10:11] op_sel_hi:[1,0,1]
	v_pk_fma_f32 v[12:13], v[64:65], s[34:35], v[12:13] op_sel_hi:[1,0,1]
	v_addc_co_u32_e32 v15, vcc, 0, v157, vcc
	global_store_dwordx4 v[14:15], v[10:13], off
	ds_read_b128 v[10:13], v158 offset:1088
	v_add_co_u32_e32 v14, vcc, s46, v154
	s_waitcnt lgkmcnt(0)
	v_pk_mul_f32 v[10:11], v[18:19], v[10:11]
	v_pk_mul_f32 v[12:13], v[20:21], v[12:13]
	s_waitcnt vmcnt(11)
	v_pk_fma_f32 v[10:11], v[58:59], s[34:35], v[10:11] op_sel_hi:[1,0,1]
	v_pk_fma_f32 v[12:13], v[60:61], s[34:35], v[12:13] op_sel_hi:[1,0,1]
	v_addc_co_u32_e32 v15, vcc, 0, v155, vcc
	global_store_dwordx4 v[14:15], v[10:13], off
	ds_read_b128 v[10:13], v158 offset:2176
	v_add_co_u32_e32 v14, vcc, s46, v150
	s_mov_b32 s46, 0x70000
	s_nop 0
	v_addc_co_u32_e32 v15, vcc, 0, v151, vcc
	s_waitcnt lgkmcnt(0)
	v_pk_mul_f32 v[10:11], v[18:19], v[10:11]
	v_pk_mul_f32 v[12:13], v[20:21], v[12:13]
	s_waitcnt vmcnt(11)
	v_pk_fma_f32 v[10:11], v[54:55], s[34:35], v[10:11] op_sel_hi:[1,0,1]
	v_pk_fma_f32 v[12:13], v[56:57], s[34:35], v[12:13] op_sel_hi:[1,0,1]
	global_store_dwordx4 v[14:15], v[10:13], off
	ds_write2_b32 v165, v30, v34 offset1:16
	ds_write2_b32 v165, v31, v35 offset0:68 offset1:84
	ds_write2_b32 v165, v32, v36 offset0:136 offset1:152
	ds_write2_b32 v165, v33, v37 offset0:204 offset1:220
	ds_write2_b32 v165, v22, v26 offset0:32 offset1:48
	ds_write2_b32 v165, v23, v27 offset0:100 offset1:116
	ds_write2_b32 v165, v24, v28 offset0:168 offset1:184
	ds_write2_b32 v165, v25, v29 offset0:236 offset1:252
	v_add_co_u32_e32 v10, vcc, s46, v162
	s_nop 1
	v_addc_co_u32_e32 v11, vcc, 0, v163, vcc
	global_load_dwordx4 v[10:13], v[10:11], off
	v_add_co_u32_e32 v14, vcc, s2, v162
	s_mov_b32 s2, 0x78000
	s_nop 0
	v_addc_co_u32_e32 v15, vcc, 0, v163, vcc
	global_load_dwordx4 v[30:33], v[14:15], off
	v_add_co_u32_e32 v14, vcc, s2, v162
	s_mov_b32 s2, 0x7c000
	s_nop 0
	v_addc_co_u32_e32 v15, vcc, 0, v163, vcc
	global_load_dwordx4 v[26:29], v[14:15], off
	v_add_co_u32_e32 v14, vcc, s2, v162
	s_nop 1
	v_addc_co_u32_e32 v15, vcc, 0, v163, vcc
	global_load_dwordx4 v[22:25], v[14:15], off
	ds_read_b128 v[14:17], v164
	v_add_co_u32_e32 v34, vcc, s39, v152
	s_waitcnt lgkmcnt(0)
; template <int EPI>
; DI void gemm_phase(const P& p, int l, const u16* __restrict__ A, const u16* __restrict__ Bt, int mpx, char* lds) {
;     ...
;     for (int mi = 0; mi < 8; ++mi) {
;       float4 xv[4];
; #pragma unroll
;       for (int i = 0; i < 4; ++i) xv[i] = xn[i];
;       if (mi < 7) {
; #pragma unroll
;         for (int i = 0; i < 4; ++i) xn[i] = *(const float4*)(xr + (size_t)((mi + 1) * 16 + rr0 + 4 * i) * 1024 + c4);
;       }
; #pragma unroll
;       for (int ni = 0; ni < 4; ++ni)
; #pragma unroll
;         for (int j = 0; j < 4; ++j) Cw[(g * 4 + j) * 68 + ni * 16 + r] = acc[mi][ni][j];
;       __builtin_amdgcn_fence(__ATOMIC_RELEASE, "wavefront");
; #pragma unroll
;       for (int i = 0; i < 4; ++i) {
;         const int row = rr0 + 4 * i;
;         const float4 a = *(const float4*)&Cw[row * 68 + c4];
;         float4 z;
;         z.x = alpha * xv[i].x + gt.x * a.x;
;         z.y = alpha * xv[i].y + gt.y * a.y;
;         z.z = alpha * xv[i].z + gt.z * a.z;
;         z.w = alpha * xv[i].w + gt.w * a.w;
;         *(float4*)(Z + (size_t)(mi * 16 + row) * 1024 + c4) = z;
;       }
;     ...
;   if (!has_next) break;
;   t = tn; m0 = m1; n0 = n1; Ag = Agn; Bg = Bgn;
	v_pk_mul_f32 v[14:15], v[18:19], v[14:15]
	v_pk_mul_f32 v[16:17], v[20:21], v[16:17]
	s_waitcnt vmcnt(11)
	v_pk_fma_f32 v[14:15], v[50:51], s[34:35], v[14:15] op_sel_hi:[1,0,1]
	v_pk_fma_f32 v[16:17], v[52:53], s[34:35], v[16:17] op_sel_hi:[1,0,1]
	v_addc_co_u32_e32 v35, vcc, 0, v153, vcc
	global_store_dwordx4 v[34:35], v[14:17], off
	ds_read_b128 v[14:17], v158
	v_add_co_u32_e32 v34, vcc, s39, v156
	s_waitcnt lgkmcnt(0)
	v_pk_mul_f32 v[14:15], v[18:19], v[14:15]
	v_pk_mul_f32 v[16:17], v[20:21], v[16:17]
	s_waitcnt vmcnt(11)
	v_pk_fma_f32 v[14:15], v[46:47], s[34:35], v[14:15] op_sel_hi:[1,0,1]
	v_pk_fma_f32 v[16:17], v[48:49], s[34:35], v[16:17] op_sel_hi:[1,0,1]
	v_addc_co_u32_e32 v35, vcc, 0, v157, vcc
	global_store_dwordx4 v[34:35], v[14:17], off
	ds_read_b128 v[14:17], v158 offset:1088
	v_add_co_u32_e32 v34, vcc, s39, v154
	s_waitcnt lgkmcnt(0)
	v_pk_mul_f32 v[14:15], v[18:19], v[14:15]
	v_pk_mul_f32 v[16:17], v[20:21], v[16:17]
	s_waitcnt vmcnt(11)
	v_pk_fma_f32 v[14:15], v[42:43], s[34:35], v[14:15] op_sel_hi:[1,0,1]
	v_pk_fma_f32 v[16:17], v[44:45], s[34:35], v[16:17] op_sel_hi:[1,0,1]
	v_addc_co_u32_e32 v35, vcc, 0, v155, vcc
	global_store_dwordx4 v[34:35], v[14:17], off
	ds_read_b128 v[14:17], v158 offset:2176
	v_add_co_u32_e32 v34, vcc, s39, v150
	s_waitcnt lgkmcnt(0)
	v_pk_mul_f32 v[14:15], v[18:19], v[14:15]
	v_pk_mul_f32 v[16:17], v[20:21], v[16:17]
	s_waitcnt vmcnt(11)
	v_pk_fma_f32 v[14:15], v[38:39], s[34:35], v[14:15] op_sel_hi:[1,0,1]
	v_pk_fma_f32 v[16:17], v[40:41], s[34:35], v[16:17] op_sel_hi:[1,0,1]
	v_addc_co_u32_e32 v35, vcc, 0, v151, vcc
	global_store_dwordx4 v[34:35], v[14:17], off
	ds_write2_b32 v165, v166, v170 offset1:16
	ds_write2_b32 v165, v167, v171 offset0:68 offset1:84
	ds_write2_b32 v165, v168, v172 offset0:136 offset1:152
	ds_write2_b32 v165, v169, v173 offset0:204 offset1:220
	ds_write2_b32 v165, v2, v6 offset0:32 offset1:48
	ds_write2_b32 v165, v3, v7 offset0:100 offset1:116
	ds_write2_b32 v165, v4, v8 offset0:168 offset1:184
	ds_write2_b32 v165, v5, v9 offset0:236 offset1:252
	ds_read_b128 v[2:5], v164
	v_add_co_u32_e32 v6, vcc, s46, v152
	s_waitcnt lgkmcnt(0)
	v_pk_mul_f32 v[2:3], v[18:19], v[2:3]
	v_pk_mul_f32 v[4:5], v[20:21], v[4:5]
	v_addc_co_u32_e32 v7, vcc, 0, v153, vcc
	s_waitcnt vmcnt(7)
	v_pk_fma_f32 v[2:3], v[10:11], s[34:35], v[2:3] op_sel_hi:[1,0,1]
	v_pk_fma_f32 v[4:5], v[12:13], s[34:35], v[4:5] op_sel_hi:[1,0,1]
	global_store_dwordx4 v[6:7], v[2:5], off
	ds_read_b128 v[2:5], v158
	v_add_co_u32_e32 v6, vcc, s46, v156
	s_waitcnt lgkmcnt(0)
	v_pk_mul_f32 v[2:3], v[18:19], v[2:3]
	v_pk_mul_f32 v[4:5], v[20:21], v[4:5]
	s_waitcnt vmcnt(7)
	v_pk_fma_f32 v[2:3], v[30:31], s[34:35], v[2:3] op_sel_hi:[1,0,1]
	v_pk_fma_f32 v[4:5], v[32:33], s[34:35], v[4:5] op_sel_hi:[1,0,1]
	v_addc_co_u32_e32 v7, vcc, 0, v157, vcc
	global_store_dwordx4 v[6:7], v[2:5], off
	ds_read_b128 v[2:5], v158 offset:1088
	v_add_co_u32_e32 v6, vcc, s46, v154
	s_mov_b64 s[46:47], s[44:45]
	s_nop 0
	v_addc_co_u32_e32 v7, vcc, 0, v155, vcc
	s_waitcnt lgkmcnt(0)
	v_pk_mul_f32 v[2:3], v[18:19], v[2:3]
	v_pk_mul_f32 v[4:5], v[20:21], v[4:5]
	s_waitcnt vmcnt(7)
	v_pk_fma_f32 v[2:3], v[26:27], s[34:35], v[2:3] op_sel_hi:[1,0,1]
	v_pk_fma_f32 v[4:5], v[28:29], s[34:35], v[4:5] op_sel_hi:[1,0,1]
	global_store_dwordx4 v[6:7], v[2:5], off
	ds_read_b128 v[2:5], v158 offset:2176
	v_add_co_u32_e32 v6, vcc, 0x70000, v150
	s_waitcnt lgkmcnt(0)
	v_pk_mul_f32 v[2:3], v[18:19], v[2:3]
	v_pk_mul_f32 v[4:5], v[20:21], v[4:5]
	v_addc_co_u32_e32 v7, vcc, 0, v151, vcc
	s_waitcnt vmcnt(7)
	v_pk_fma_f32 v[2:3], v[22:23], s[34:35], v[2:3] op_sel_hi:[1,0,1]
	v_pk_fma_f32 v[4:5], v[24:25], s[34:35], v[4:5] op_sel_hi:[1,0,1]
	s_and_b64 vcc, exec, s[40:41]
	global_store_dwordx4 v[6:7], v[2:5], off
	s_cbranch_vccz .LBB0_69
	v_mov_b32_e32 v236, 0x358637bd

; template <int EPI>
; DI void gemm_phase(const P& p, int l, const u16* __restrict__ A, const u16* __restrict__ Bt, int mpx, char* lds) {
;     ...
;   while (true) {
;   const int tn = t + 1;
;   int m1 = 0, n1 = 0;
;   const bool has_next = tile_coords<EPI>(tn, mpx, m1, n1);
;   const u16* Agn = A + (size_t)m1 * 1024;
;   const u16* Bgn = Bt + (size_t)n1 * 1024;
;   f32x4 acc[8][4];
; #pragma unroll
;   for (int i = 0; i < 8; ++i)
; #pragma unroll
;     for (int j = 0; j < 4; ++j) acc[i][j] = zero4();
;   {
;   const int lane = tid & 63, w = tid >> 6, r = lane & 15, g = lane >> 4, wm = w >> 2, wn = w & 3;
;   __syncthreads();
;   GLOAD(Ag, Bg, 64)
;   __builtin_amdgcn_sched_barrier(0);
;   GCOMPUTE_KS(As0, Bs0, 0)
;   __builtin_amdgcn_sched_barrier(0);
;   GSTORE(As1, Bs1)
;   GLOAD(Ag, Bg, 128)
;   __builtin_amdgcn_sched_barrier(0);
;   GCOMPUTE_KS(As0, Bs0, 1)
.LBB0_81:
	v_lshl_add_u64 v[138:139], s[40:41], 0, v[196:197]
	v_add_co_u32_e32 v140, vcc, s33, v138
	v_lshl_add_u64 v[146:147], s[0:1], 0, v[196:197]
	s_nop 0
	v_addc_co_u32_e32 v141, vcc, 0, v139, vcc
	v_add_co_u32_e32 v142, vcc, s35, v138
	s_waitcnt lgkmcnt(0)
	s_nop 0
	v_addc_co_u32_e32 v143, vcc, 0, v139, vcc
	v_add_co_u32_e32 v144, vcc, s39, v138
	s_barrier
	s_nop 0
	v_addc_co_u32_e32 v145, vcc, 0, v139, vcc
	v_add_co_u32_e32 v150, vcc, s33, v146
	s_nop 1
	v_addc_co_u32_e32 v151, vcc, 0, v147, vcc
	v_add_co_u32_e32 v154, vcc, s35, v146
	global_load_dwordx4 v[2:5], v[138:139], off offset:128
	global_load_dwordx4 v[6:9], v[140:141], off offset:128
	v_addc_co_u32_e32 v155, vcc, 0, v147, vcc
	v_add_co_u32_e32 v158, vcc, s39, v146
	global_load_dwordx4 v[10:13], v[142:143], off offset:128
	global_load_dwordx4 v[14:17], v[144:145], off offset:128
	global_load_dwordx4 v[18:21], v[146:147], off offset:128
	global_load_dwordx4 v[22:25], v[150:151], off offset:128
	v_addc_co_u32_e32 v159, vcc, 0, v147, vcc
	global_load_dwordx4 v[26:29], v[154:155], off offset:128
	global_load_dwordx4 v[30:33], v[158:159], off offset:128
	s_mov_b32 s57, s3
	s_lshl_b64 s[42:43], s[56:57], 11
	s_lshl_b32 s2, s51, 11
	s_add_u32 s58, s16, s42
	s_addc_u32 s59, s17, s43
	ds_read_b128 v[34:37], v205
	ds_read_b128 v[38:41], v204 offset:32768
	ds_read_b128 v[42:45], v204 offset:34816
	ds_read_b128 v[46:49], v205 offset:2048
	ds_read_b128 v[58:61], v204 offset:36864
	ds_read_b128 v[62:65], v204 offset:38912
	ds_read_b128 v[82:85], v205 offset:4096
	ds_read_b128 v[86:89], v205 offset:6144
	ds_read_b128 v[114:117], v205 offset:8192
	ds_read_b128 v[118:121], v205 offset:10240
	s_waitcnt vmcnt(25)
	ds_read_b128 v[130:133], v205 offset:12288
	s_waitcnt vmcnt(24)
	ds_read_b128 v[134:137], v205 offset:14336
	s_waitcnt lgkmcnt(10)
	v_mfma_f32_16x16x32_bf16 v[50:53], v[34:37], v[38:41], 0
	s_add_u32 s60, s24, s2
	s_addc_u32 s61, s25, 0
	s_waitcnt lgkmcnt(9)
	v_mfma_f32_16x16x32_bf16 v[54:57], v[34:37], v[42:45], 0
	s_waitcnt lgkmcnt(7)
	v_mfma_f32_16x16x32_bf16 v[66:69], v[34:37], v[58:61], 0
	s_waitcnt lgkmcnt(6)
	v_mfma_f32_16x16x32_bf16 v[34:37], v[34:37], v[62:65], 0
	v_mfma_f32_16x16x32_bf16 v[70:73], v[46:49], v[38:41], 0
	v_mfma_f32_16x16x32_bf16 v[74:77], v[46:49], v[42:45], 0
	v_mfma_f32_16x16x32_bf16 v[78:81], v[46:49], v[58:61], 0
	v_mfma_f32_16x16x32_bf16 v[46:49], v[46:49], v[62:65], 0
	s_waitcnt lgkmcnt(5)
	v_mfma_f32_16x16x32_bf16 v[90:93], v[82:85], v[38:41], 0
	v_mfma_f32_16x16x32_bf16 v[94:97], v[82:85], v[42:45], 0
	v_mfma_f32_16x16x32_bf16 v[98:101], v[82:85], v[58:61], 0
	v_mfma_f32_16x16x32_bf16 v[82:85], v[82:85], v[62:65], 0
	s_waitcnt lgkmcnt(4)
	v_mfma_f32_16x16x32_bf16 v[102:105], v[86:89], v[38:41], 0
	v_mfma_f32_16x16x32_bf16 v[106:109], v[86:89], v[42:45], 0
	v_mfma_f32_16x16x32_bf16 v[110:113], v[86:89], v[58:61], 0
	v_mfma_f32_16x16x32_bf16 v[86:89], v[86:89], v[62:65], 0
	s_waitcnt lgkmcnt(3)
	v_mfma_f32_16x16x32_bf16 v[122:125], v[114:117], v[38:41], 0
	v_mfma_f32_16x16x32_bf16 v[126:129], v[114:117], v[42:45], 0
	v_mfma_f32_16x16x32_bf16 v[162:165], v[114:117], v[58:61], 0
	v_mfma_f32_16x16x32_bf16 v[114:117], v[114:117], v[62:65], 0
	s_waitcnt lgkmcnt(2)
	v_mfma_f32_16x16x32_bf16 v[166:169], v[118:121], v[38:41], 0
	v_mfma_f32_16x16x32_bf16 v[170:173], v[118:121], v[42:45], 0
	v_mfma_f32_16x16x32_bf16 v[174:177], v[118:121], v[58:61], 0
	v_mfma_f32_16x16x32_bf16 v[118:121], v[118:121], v[62:65], 0
	s_waitcnt lgkmcnt(1)
	v_mfma_f32_16x16x32_bf16 v[178:181], v[130:133], v[38:41], 0
	v_mfma_f32_16x16x32_bf16 v[182:185], v[130:133], v[42:45], 0
	v_mfma_f32_16x16x32_bf16 v[186:189], v[130:133], v[58:61], 0
	v_mfma_f32_16x16x32_bf16 v[190:193], v[130:133], v[62:65], 0
	s_waitcnt lgkmcnt(0)
	v_mfma_f32_16x16x32_bf16 v[234:237], v[134:137], v[38:41], 0
	v_mfma_f32_16x16x32_bf16 v[238:241], v[134:137], v[42:45], 0
	v_mfma_f32_16x16x32_bf16 v[242:245], v[134:137], v[58:61], 0
	v_mfma_f32_16x16x32_bf16 v[246:249], v[134:137], v[62:65], 0
	s_waitcnt vmcnt(7)
	ds_write_b128 v202, v[2:5]
	s_waitcnt vmcnt(6)
	ds_write_b128 v227, v[6:9]
	s_waitcnt vmcnt(5)
	ds_write_b128 v228, v[10:13]
	s_waitcnt vmcnt(4)
	ds_write_b128 v229, v[14:17]
	s_waitcnt vmcnt(3)
	ds_write_b128 v203, v[18:21]
	s_waitcnt vmcnt(2)
	ds_write_b128 v230, v[22:25]
	s_waitcnt vmcnt(1)
	ds_write_b128 v231, v[26:29]
	s_waitcnt vmcnt(0)
	ds_write_b128 v232, v[30:33]
	global_load_dwordx4 v[130:133], v[138:139], off offset:256
	global_load_dwordx4 v[134:137], v[140:141], off offset:256
	s_nop 0
	global_load_dwordx4 v[138:141], v[142:143], off offset:256
	s_nop 0
	global_load_dwordx4 v[142:145], v[144:145], off offset:256
	s_nop 0
	global_load_dwordx4 v[146:149], v[146:147], off offset:256
	s_nop 0
	global_load_dwordx4 v[150:153], v[150:151], off offset:256
	s_nop 0
	global_load_dwordx4 v[154:157], v[154:155], off offset:256
	s_nop 0
	global_load_dwordx4 v[158:161], v[158:159], off offset:256
	ds_read_b128 v[2:5], v207
	ds_read_b128 v[250:253], v206 offset:32768
	ds_read_b128 v[216:219], v206 offset:34816
	ds_read_b128 v[212:215], v206 offset:36864
	ds_read_b128 v[220:223], v206 offset:38912
	s_waitcnt lgkmcnt(3)
	v_mfma_f32_16x16x32_bf16 v[6:9], v[2:5], v[250:253], v[50:53]
	s_waitcnt lgkmcnt(2)
	v_mfma_f32_16x16x32_bf16 v[10:13], v[2:5], v[216:219], v[54:57]
	s_waitcnt lgkmcnt(1)
	v_mfma_f32_16x16x32_bf16 v[14:17], v[2:5], v[212:215], v[66:69]
	s_waitcnt lgkmcnt(0)
	v_mfma_f32_16x16x32_bf16 v[18:21], v[2:5], v[220:223], v[34:37]
	ds_read_b128 v[2:5], v207 offset:2048
	s_waitcnt lgkmcnt(0)
; #define GCOMPUTE(AS, BS) GCOMPUTE_KS(AS, BS, 0) GCOMPUTE_KS(AS, BS, 1)
; template <int EPI>
; DI void gemm_phase(const P& p, int l, const u16* __restrict__ A, const u16* __restrict__ Bt, int mpx, char* lds) {
;     ...
;   GCOMPUTE_KS(As0, Bs0, 1)
;   __builtin_amdgcn_sched_barrier(0);
; #pragma unroll 1
;   for (int kk = 1; kk < 15; kk += 2) {
;     __syncthreads();
;     GSTORE(As0, Bs0)
;     GLOAD(Ag, Bg, (kk + 2) * 64)
;     __builtin_amdgcn_sched_barrier(0);
;     GCOMPUTE(As1, Bs1)
	v_mfma_f32_16x16x32_bf16 v[22:25], v[2:5], v[250:253], v[70:73]
	v_mfma_f32_16x16x32_bf16 v[26:29], v[2:5], v[216:219], v[74:77]
	v_mfma_f32_16x16x32_bf16 v[30:33], v[2:5], v[212:215], v[78:81]
	v_mfma_f32_16x16x32_bf16 v[34:37], v[2:5], v[220:223], v[46:49]
	ds_read_b128 v[2:5], v207 offset:4096
	s_waitcnt lgkmcnt(0)
	v_mfma_f32_16x16x32_bf16 v[38:41], v[2:5], v[250:253], v[90:93]
	v_mfma_f32_16x16x32_bf16 v[42:45], v[2:5], v[216:219], v[94:97]
	v_mfma_f32_16x16x32_bf16 v[46:49], v[2:5], v[212:215], v[98:101]
	v_mfma_f32_16x16x32_bf16 v[50:53], v[2:5], v[220:223], v[82:85]
	ds_read_b128 v[2:5], v207 offset:6144
	s_waitcnt lgkmcnt(0)
	v_mfma_f32_16x16x32_bf16 v[54:57], v[2:5], v[250:253], v[102:105]
	v_mfma_f32_16x16x32_bf16 v[58:61], v[2:5], v[216:219], v[106:109]
	v_mfma_f32_16x16x32_bf16 v[62:65], v[2:5], v[212:215], v[110:113]
	v_mfma_f32_16x16x32_bf16 v[66:69], v[2:5], v[220:223], v[86:89]
	ds_read_b128 v[2:5], v207 offset:8192
	s_waitcnt lgkmcnt(0)
	v_mfma_f32_16x16x32_bf16 v[70:73], v[2:5], v[250:253], v[122:125]
	v_mfma_f32_16x16x32_bf16 v[74:77], v[2:5], v[216:219], v[126:129]
	v_mfma_f32_16x16x32_bf16 v[78:81], v[2:5], v[212:215], v[162:165]
	v_mfma_f32_16x16x32_bf16 v[82:85], v[2:5], v[220:223], v[114:117]
	ds_read_b128 v[2:5], v207 offset:10240
	s_waitcnt lgkmcnt(0)
	v_mfma_f32_16x16x32_bf16 v[86:89], v[2:5], v[250:253], v[166:169]
	v_mfma_f32_16x16x32_bf16 v[90:93], v[2:5], v[216:219], v[170:173]
	v_mfma_f32_16x16x32_bf16 v[94:97], v[2:5], v[212:215], v[174:177]
	v_mfma_f32_16x16x32_bf16 v[98:101], v[2:5], v[220:223], v[118:121]
	ds_read_b128 v[2:5], v207 offset:12288
	s_waitcnt lgkmcnt(0)
	v_mfma_f32_16x16x32_bf16 v[102:105], v[2:5], v[250:253], v[178:181]
	v_mfma_f32_16x16x32_bf16 v[106:109], v[2:5], v[216:219], v[182:185]
	v_mfma_f32_16x16x32_bf16 v[110:113], v[2:5], v[212:215], v[186:189]
	v_mfma_f32_16x16x32_bf16 v[114:117], v[2:5], v[220:223], v[190:193]
	ds_read_b128 v[2:5], v207 offset:14336
	s_waitcnt lgkmcnt(0)
	v_mfma_f32_16x16x32_bf16 v[118:121], v[2:5], v[250:253], v[234:237]
	v_mfma_f32_16x16x32_bf16 v[122:125], v[2:5], v[216:219], v[238:241]
	v_mfma_f32_16x16x32_bf16 v[126:129], v[2:5], v[212:215], v[242:245]
	v_mfma_f32_16x16x32_bf16 v[2:5], v[2:5], v[220:223], v[246:249]
	s_mov_b32 s49, 1
	s_movk_i32 s47, 0x100
	s_mov_b64 s[42:43], s[0:1]
	s_mov_b64 s[44:45], s[40:41]
	v_add_u32_e32 v208, s33, v196
	v_add_u32_e32 v209, s35, v196
	v_add_u32_e32 v210, s39, v196
	s_barrier
	ds_read_b128 v[212:215], v198
	ds_read_b128 v[216:219], v198 offset:2048
	ds_read_b128 v[220:223], v198 offset:4096
	ds_read_b128 v[234:237], v198 offset:6144
	ds_read_b128 v[238:241], v199
	ds_read_b128 v[242:245], v199 offset:2048
	ds_read_b128 v[246:249], v199 offset:4096
	ds_read_b128 v[250:253], v199 offset:6144
	global_load_dwordx4 v[162:165], v196, s[44:45] offset:384
	global_load_dwordx4 v[166:169], v208, s[44:45] offset:384
	global_load_dwordx4 v[170:173], v209, s[44:45] offset:384
	global_load_dwordx4 v[174:177], v210, s[44:45] offset:384
	global_load_dwordx4 v[178:181], v196, s[42:43] offset:384
	global_load_dwordx4 v[182:185], v208, s[42:43] offset:384
	global_load_dwordx4 v[186:189], v209, s[42:43] offset:384
	global_load_dwordx4 v[190:193], v210, s[42:43] offset:384
.LBB0_82:
	s_add_i32 s48, s49, 2
	s_waitcnt lgkmcnt(3)
	v_mfma_f32_16x16x32_bf16 v[6:9], v[238:241], v[212:215], v[6:9]
	v_mfma_f32_16x16x32_bf16 v[10:13], v[238:241], v[216:219], v[10:13]
	v_mfma_f32_16x16x32_bf16 v[14:17], v[238:241], v[220:223], v[14:17]
	v_mfma_f32_16x16x32_bf16 v[18:21], v[238:241], v[234:237], v[18:21]
	ds_read_b128 v[238:241], v199 offset:8192
	s_waitcnt vmcnt(15)
	ds_write_b128 v201, v[130:133]
	s_waitcnt lgkmcnt(4)
	v_mfma_f32_16x16x32_bf16 v[22:25], v[242:245], v[212:215], v[22:25]
	v_mfma_f32_16x16x32_bf16 v[26:29], v[242:245], v[216:219], v[26:29]
	v_mfma_f32_16x16x32_bf16 v[30:33], v[242:245], v[220:223], v[30:33]
	v_mfma_f32_16x16x32_bf16 v[34:37], v[242:245], v[234:237], v[34:37]
	ds_read_b128 v[242:245], v199 offset:10240
	s_waitcnt vmcnt(14)
	ds_write_b128 v201, v[134:137] offset:8192
	ds_read_b128 v[130:133], v200
	s_waitcnt lgkmcnt(6)
	v_mfma_f32_16x16x32_bf16 v[38:41], v[246:249], v[212:215], v[38:41]
	v_mfma_f32_16x16x32_bf16 v[42:45], v[246:249], v[216:219], v[42:45]
	v_mfma_f32_16x16x32_bf16 v[46:49], v[246:249], v[220:223], v[46:49]
	v_mfma_f32_16x16x32_bf16 v[50:53], v[246:249], v[234:237], v[50:53]
	ds_read_b128 v[246:249], v199 offset:12288
	s_waitcnt vmcnt(13)
	ds_write_b128 v201, v[138:141] offset:16384
	ds_read_b128 v[134:137], v200 offset:2048
	s_waitcnt lgkmcnt(8)
	v_mfma_f32_16x16x32_bf16 v[54:57], v[250:253], v[212:215], v[54:57]
	v_mfma_f32_16x16x32_bf16 v[58:61], v[250:253], v[216:219], v[58:61]
	v_mfma_f32_16x16x32_bf16 v[62:65], v[250:253], v[220:223], v[62:65]
	v_mfma_f32_16x16x32_bf16 v[66:69], v[250:253], v[234:237], v[66:69]
	ds_read_b128 v[250:253], v199 offset:14336
	s_waitcnt vmcnt(12)
	ds_write_b128 v201, v[142:145] offset:24576
	ds_read_b128 v[138:141], v200 offset:4096
	s_waitcnt lgkmcnt(10)
	v_mfma_f32_16x16x32_bf16 v[70:73], v[238:241], v[212:215], v[70:73]
	v_mfma_f32_16x16x32_bf16 v[74:77], v[238:241], v[216:219], v[74:77]
	v_mfma_f32_16x16x32_bf16 v[78:81], v[238:241], v[220:223], v[78:81]
	v_mfma_f32_16x16x32_bf16 v[82:85], v[238:241], v[234:237], v[82:85]
	ds_read_b128 v[238:241], v233
	s_waitcnt vmcnt(11)
	ds_write_b128 v201, v[146:149] offset:32768
	ds_read_b128 v[142:145], v200 offset:6144
	s_waitcnt lgkmcnt(11)
	v_mfma_f32_16x16x32_bf16 v[86:89], v[242:245], v[212:215], v[86:89]
	v_mfma_f32_16x16x32_bf16 v[90:93], v[242:245], v[216:219], v[90:93]
	v_mfma_f32_16x16x32_bf16 v[94:97], v[242:245], v[220:223], v[94:97]
	v_mfma_f32_16x16x32_bf16 v[98:101], v[242:245], v[234:237], v[98:101]
	ds_read_b128 v[242:245], v233 offset:2048
	s_waitcnt vmcnt(10)
; #define GCOMPUTE(AS, BS) GCOMPUTE_KS(AS, BS, 0) GCOMPUTE_KS(AS, BS, 1)
; template <int EPI>
; DI void gemm_phase(const P& p, int l, const u16* __restrict__ A, const u16* __restrict__ Bt, int mpx, char* lds) {
;     ...
;     GCOMPUTE(As1, Bs1)
;     __builtin_amdgcn_sched_barrier(0);
;     __syncthreads();
;     GSTORE(As1, Bs1)
;     {
;       const bool in_tile = kk + 3 < 16;
;       const u16* pa = in_tile ? Ag : Agn;
;       const u16* pb = in_tile ? Bg : Bgn;
;       const int k0 = in_tile ? (kk + 3) * 64 : 0;
;       GLOAD(pa, pb, k0)
;     }
;     __builtin_amdgcn_sched_barrier(0);
;     GCOMPUTE(As0, Bs0)
	ds_write_b128 v201, v[150:153] offset:40960
	s_waitcnt lgkmcnt(10)
	v_mfma_f32_16x16x32_bf16 v[102:105], v[246:249], v[212:215], v[102:105]
	v_mfma_f32_16x16x32_bf16 v[106:109], v[246:249], v[216:219], v[106:109]
	v_mfma_f32_16x16x32_bf16 v[110:113], v[246:249], v[220:223], v[110:113]
	v_mfma_f32_16x16x32_bf16 v[114:117], v[246:249], v[234:237], v[114:117]
	ds_read_b128 v[246:249], v233 offset:4096
	s_waitcnt vmcnt(9)
	ds_write_b128 v201, v[154:157] offset:49152
	s_waitcnt lgkmcnt(9)
	v_mfma_f32_16x16x32_bf16 v[118:121], v[250:253], v[212:215], v[118:121]
	v_mfma_f32_16x16x32_bf16 v[122:125], v[250:253], v[216:219], v[122:125]
	v_mfma_f32_16x16x32_bf16 v[126:129], v[250:253], v[220:223], v[126:129]
	v_mfma_f32_16x16x32_bf16 v[2:5], v[250:253], v[234:237], v[2:5]
	ds_read_b128 v[250:253], v233 offset:6144
	s_waitcnt vmcnt(8)
	ds_write_b128 v201, v[158:161] offset:57344
	s_waitcnt lgkmcnt(6)
	v_mfma_f32_16x16x32_bf16 v[6:9], v[238:241], v[130:133], v[6:9]
	v_mfma_f32_16x16x32_bf16 v[10:13], v[238:241], v[134:137], v[10:13]
	v_mfma_f32_16x16x32_bf16 v[14:17], v[238:241], v[138:141], v[14:17]
	v_mfma_f32_16x16x32_bf16 v[18:21], v[238:241], v[142:145], v[18:21]
	ds_read_b128 v[238:241], v233 offset:8192
	s_waitcnt lgkmcnt(6)
	v_mfma_f32_16x16x32_bf16 v[22:25], v[242:245], v[130:133], v[22:25]
	v_mfma_f32_16x16x32_bf16 v[26:29], v[242:245], v[134:137], v[26:29]
	v_mfma_f32_16x16x32_bf16 v[30:33], v[242:245], v[138:141], v[30:33]
	v_mfma_f32_16x16x32_bf16 v[34:37], v[242:245], v[142:145], v[34:37]
	ds_read_b128 v[242:245], v233 offset:10240
	s_waitcnt lgkmcnt(5)
	v_mfma_f32_16x16x32_bf16 v[38:41], v[246:249], v[130:133], v[38:41]
	v_mfma_f32_16x16x32_bf16 v[42:45], v[246:249], v[134:137], v[42:45]
	v_mfma_f32_16x16x32_bf16 v[46:49], v[246:249], v[138:141], v[46:49]
	v_mfma_f32_16x16x32_bf16 v[50:53], v[246:249], v[142:145], v[50:53]
	ds_read_b128 v[246:249], v233 offset:12288
	s_waitcnt lgkmcnt(4)
	v_mfma_f32_16x16x32_bf16 v[54:57], v[250:253], v[130:133], v[54:57]
	v_mfma_f32_16x16x32_bf16 v[58:61], v[250:253], v[134:137], v[58:61]
	v_mfma_f32_16x16x32_bf16 v[62:65], v[250:253], v[138:141], v[62:65]
	v_mfma_f32_16x16x32_bf16 v[66:69], v[250:253], v[142:145], v[66:69]
	ds_read_b128 v[250:253], v233 offset:14336
	s_waitcnt lgkmcnt(3)
	v_mfma_f32_16x16x32_bf16 v[70:73], v[238:241], v[130:133], v[70:73]
	v_mfma_f32_16x16x32_bf16 v[74:77], v[238:241], v[134:137], v[74:77]
	v_mfma_f32_16x16x32_bf16 v[78:81], v[238:241], v[138:141], v[78:81]
	v_mfma_f32_16x16x32_bf16 v[82:85], v[238:241], v[142:145], v[82:85]
	s_waitcnt lgkmcnt(2)
	v_mfma_f32_16x16x32_bf16 v[86:89], v[242:245], v[130:133], v[86:89]
	v_mfma_f32_16x16x32_bf16 v[90:93], v[242:245], v[134:137], v[90:93]
	v_mfma_f32_16x16x32_bf16 v[94:97], v[242:245], v[138:141], v[94:97]
	v_mfma_f32_16x16x32_bf16 v[98:101], v[242:245], v[142:145], v[98:101]
	s_waitcnt lgkmcnt(0)
	s_cmp_lt_u32 s49, 13
	s_cselect_b64 s[62:63], -1, 0
	s_and_b64 s[62:63], s[62:63], exec
	s_cselect_b32 s2, s47, 0
	s_cselect_b32 s57, s41, s59
	s_cselect_b32 s64, s40, s58
	s_cselect_b32 s67, s1, s61
	s_cselect_b32 s68, s0, s60
	s_lshl_b64 s[62:63], s[2:3], 1
	s_add_u32 s64, s64, s62
	s_addc_u32 s65, s57, s63
	s_add_u32 s62, s68, s62
	s_addc_u32 s63, s67, s63
	s_barrier
	ds_read_b128 v[212:215], v204 offset:32768
	ds_read_b128 v[216:219], v204 offset:34816
	ds_read_b128 v[220:223], v204 offset:36864
	ds_read_b128 v[234:237], v204 offset:38912
	ds_read_b128 v[238:241], v205
	ds_read_b128 v[242:245], v205 offset:2048
	v_mfma_f32_16x16x32_bf16 v[102:105], v[246:249], v[130:133], v[102:105]
	v_mfma_f32_16x16x32_bf16 v[106:109], v[246:249], v[134:137], v[106:109]
	v_mfma_f32_16x16x32_bf16 v[110:113], v[246:249], v[138:141], v[110:113]
	v_mfma_f32_16x16x32_bf16 v[114:117], v[246:249], v[142:145], v[114:117]
	ds_read_b128 v[246:249], v205 offset:4096
	v_mfma_f32_16x16x32_bf16 v[118:121], v[250:253], v[130:133], v[118:121]
	v_mfma_f32_16x16x32_bf16 v[122:125], v[250:253], v[134:137], v[122:125]
	v_mfma_f32_16x16x32_bf16 v[126:129], v[250:253], v[138:141], v[126:129]
	v_mfma_f32_16x16x32_bf16 v[2:5], v[250:253], v[142:145], v[2:5]
	ds_read_b128 v[250:253], v205 offset:6144
	global_load_dwordx4 v[130:133], v196, s[64:65]
	global_load_dwordx4 v[134:137], v208, s[64:65]
	global_load_dwordx4 v[138:141], v209, s[64:65]
	global_load_dwordx4 v[142:145], v210, s[64:65]
	global_load_dwordx4 v[146:149], v196, s[62:63]
	global_load_dwordx4 v[150:153], v208, s[62:63]
	global_load_dwordx4 v[154:157], v209, s[62:63]
	global_load_dwordx4 v[158:161], v210, s[62:63]
	s_waitcnt lgkmcnt(3)
	v_mfma_f32_16x16x32_bf16 v[6:9], v[238:241], v[212:215], v[6:9]
	v_mfma_f32_16x16x32_bf16 v[10:13], v[238:241], v[216:219], v[10:13]
	v_mfma_f32_16x16x32_bf16 v[14:17], v[238:241], v[220:223], v[14:17]
	v_mfma_f32_16x16x32_bf16 v[18:21], v[238:241], v[234:237], v[18:21]
	ds_read_b128 v[238:241], v205 offset:8192
	s_waitcnt vmcnt(15)
	ds_write_b128 v202, v[162:165]
	s_waitcnt lgkmcnt(4)
	v_mfma_f32_16x16x32_bf16 v[22:25], v[242:245], v[212:215], v[22:25]
	v_mfma_f32_16x16x32_bf16 v[26:29], v[242:245], v[216:219], v[26:29]
	v_mfma_f32_16x16x32_bf16 v[30:33], v[242:245], v[220:223], v[30:33]
	v_mfma_f32_16x16x32_bf16 v[34:37], v[242:245], v[234:237], v[34:37]
	ds_read_b128 v[242:245], v205 offset:10240
	s_waitcnt vmcnt(14)
	ds_write_b128 v227, v[166:169]
	ds_read_b128 v[162:165], v206 offset:32768
	s_waitcnt lgkmcnt(6)
	v_mfma_f32_16x16x32_bf16 v[38:41], v[246:249], v[212:215], v[38:41]
	v_mfma_f32_16x16x32_bf16 v[42:45], v[246:249], v[216:219], v[42:45]
	v_mfma_f32_16x16x32_bf16 v[46:49], v[246:249], v[220:223], v[46:49]
	v_mfma_f32_16x16x32_bf16 v[50:53], v[246:249], v[234:237], v[50:53]
	ds_read_b128 v[246:249], v205 offset:12288
	s_waitcnt vmcnt(13)
; #define GCOMPUTE(AS, BS) GCOMPUTE_KS(AS, BS, 0) GCOMPUTE_KS(AS, BS, 1)
; template <int EPI>
; DI void gemm_phase(const P& p, int l, const u16* __restrict__ A, const u16* __restrict__ Bt, int mpx, char* lds) {
;     ...
;       GLOAD(pa, pb, k0)
;     }
;     __builtin_amdgcn_sched_barrier(0);
;     GCOMPUTE(As0, Bs0)
;     __builtin_amdgcn_sched_barrier(0);
;   }
	ds_write_b128 v228, v[170:173]
	ds_read_b128 v[166:169], v206 offset:34816
	s_waitcnt lgkmcnt(8)
	v_mfma_f32_16x16x32_bf16 v[54:57], v[250:253], v[212:215], v[54:57]
	v_mfma_f32_16x16x32_bf16 v[58:61], v[250:253], v[216:219], v[58:61]
	v_mfma_f32_16x16x32_bf16 v[62:65], v[250:253], v[220:223], v[62:65]
	v_mfma_f32_16x16x32_bf16 v[66:69], v[250:253], v[234:237], v[66:69]
	ds_read_b128 v[250:253], v205 offset:14336
	s_waitcnt vmcnt(12)
	ds_write_b128 v229, v[174:177]
	ds_read_b128 v[170:173], v206 offset:36864
	s_waitcnt lgkmcnt(10)
	v_mfma_f32_16x16x32_bf16 v[70:73], v[238:241], v[212:215], v[70:73]
	v_mfma_f32_16x16x32_bf16 v[74:77], v[238:241], v[216:219], v[74:77]
	v_mfma_f32_16x16x32_bf16 v[78:81], v[238:241], v[220:223], v[78:81]
	v_mfma_f32_16x16x32_bf16 v[82:85], v[238:241], v[234:237], v[82:85]
	ds_read_b128 v[238:241], v207
	s_waitcnt vmcnt(11)
	ds_write_b128 v203, v[178:181]
	ds_read_b128 v[174:177], v206 offset:38912
	s_waitcnt lgkmcnt(11)
	v_mfma_f32_16x16x32_bf16 v[86:89], v[242:245], v[212:215], v[86:89]
	v_mfma_f32_16x16x32_bf16 v[90:93], v[242:245], v[216:219], v[90:93]
	v_mfma_f32_16x16x32_bf16 v[94:97], v[242:245], v[220:223], v[94:97]
	v_mfma_f32_16x16x32_bf16 v[98:101], v[242:245], v[234:237], v[98:101]
	ds_read_b128 v[242:245], v207 offset:2048
	s_waitcnt vmcnt(10)
	ds_write_b128 v230, v[182:185]
	s_waitcnt lgkmcnt(10)
	v_mfma_f32_16x16x32_bf16 v[102:105], v[246:249], v[212:215], v[102:105]
	v_mfma_f32_16x16x32_bf16 v[106:109], v[246:249], v[216:219], v[106:109]
	v_mfma_f32_16x16x32_bf16 v[110:113], v[246:249], v[220:223], v[110:113]
	v_mfma_f32_16x16x32_bf16 v[114:117], v[246:249], v[234:237], v[114:117]
	ds_read_b128 v[246:249], v207 offset:4096
	s_waitcnt vmcnt(9)
	ds_write_b128 v231, v[186:189]
	s_waitcnt lgkmcnt(9)
	v_mfma_f32_16x16x32_bf16 v[118:121], v[250:253], v[212:215], v[118:121]
	v_mfma_f32_16x16x32_bf16 v[122:125], v[250:253], v[216:219], v[122:125]
	v_mfma_f32_16x16x32_bf16 v[126:129], v[250:253], v[220:223], v[126:129]
	v_mfma_f32_16x16x32_bf16 v[2:5], v[250:253], v[234:237], v[2:5]
	ds_read_b128 v[250:253], v207 offset:6144
	s_waitcnt vmcnt(8)
	ds_write_b128 v232, v[190:193]
	s_waitcnt lgkmcnt(6)
	v_mfma_f32_16x16x32_bf16 v[6:9], v[238:241], v[162:165], v[6:9]
	v_mfma_f32_16x16x32_bf16 v[10:13], v[238:241], v[166:169], v[10:13]
	v_mfma_f32_16x16x32_bf16 v[14:17], v[238:241], v[170:173], v[14:17]
	v_mfma_f32_16x16x32_bf16 v[18:21], v[238:241], v[174:177], v[18:21]
	ds_read_b128 v[238:241], v207 offset:8192
	s_waitcnt lgkmcnt(6)
	v_mfma_f32_16x16x32_bf16 v[22:25], v[242:245], v[162:165], v[22:25]
	v_mfma_f32_16x16x32_bf16 v[26:29], v[242:245], v[166:169], v[26:29]
	v_mfma_f32_16x16x32_bf16 v[30:33], v[242:245], v[170:173], v[30:33]
	v_mfma_f32_16x16x32_bf16 v[34:37], v[242:245], v[174:177], v[34:37]
	ds_read_b128 v[242:245], v207 offset:10240
	s_waitcnt lgkmcnt(5)
	v_mfma_f32_16x16x32_bf16 v[38:41], v[246:249], v[162:165], v[38:41]
	v_mfma_f32_16x16x32_bf16 v[42:45], v[246:249], v[166:169], v[42:45]
	v_mfma_f32_16x16x32_bf16 v[46:49], v[246:249], v[170:173], v[46:49]
	v_mfma_f32_16x16x32_bf16 v[50:53], v[246:249], v[174:177], v[50:53]
	ds_read_b128 v[246:249], v207 offset:12288
	s_waitcnt lgkmcnt(4)
	v_mfma_f32_16x16x32_bf16 v[54:57], v[250:253], v[162:165], v[54:57]
	v_mfma_f32_16x16x32_bf16 v[58:61], v[250:253], v[166:169], v[58:61]
	v_mfma_f32_16x16x32_bf16 v[62:65], v[250:253], v[170:173], v[62:65]
	v_mfma_f32_16x16x32_bf16 v[66:69], v[250:253], v[174:177], v[66:69]
	ds_read_b128 v[250:253], v207 offset:14336
	s_waitcnt lgkmcnt(3)
	v_mfma_f32_16x16x32_bf16 v[70:73], v[238:241], v[162:165], v[70:73]
	v_mfma_f32_16x16x32_bf16 v[74:77], v[238:241], v[166:169], v[74:77]
	v_mfma_f32_16x16x32_bf16 v[78:81], v[238:241], v[170:173], v[78:81]
	v_mfma_f32_16x16x32_bf16 v[82:85], v[238:241], v[174:177], v[82:85]
	s_waitcnt lgkmcnt(2)
	v_mfma_f32_16x16x32_bf16 v[86:89], v[242:245], v[162:165], v[86:89]
	v_mfma_f32_16x16x32_bf16 v[90:93], v[242:245], v[166:169], v[90:93]
	v_mfma_f32_16x16x32_bf16 v[94:97], v[242:245], v[170:173], v[94:97]
	v_mfma_f32_16x16x32_bf16 v[98:101], v[242:245], v[174:177], v[98:101]
	s_waitcnt lgkmcnt(0)
	s_addk_i32 s47, 0x80
	s_add_u32 s44, s44, 0x100
	s_addc_u32 s45, s45, 0
	s_add_u32 s42, s42, 0x100
	s_addc_u32 s43, s43, 0
	s_cmp_gt_u32 s49, 12
	s_mov_b32 s49, s48
	s_cbranch_scc1 .Lgemm_in_exit
	s_barrier
	ds_read_b128 v[212:215], v198
	ds_read_b128 v[216:219], v198 offset:2048
	ds_read_b128 v[220:223], v198 offset:4096
	ds_read_b128 v[234:237], v198 offset:6144
	ds_read_b128 v[238:241], v199
	ds_read_b128 v[242:245], v199 offset:2048
	v_mfma_f32_16x16x32_bf16 v[102:105], v[246:249], v[162:165], v[102:105]
	v_mfma_f32_16x16x32_bf16 v[106:109], v[246:249], v[166:169], v[106:109]
	v_mfma_f32_16x16x32_bf16 v[110:113], v[246:249], v[170:173], v[110:113]
	v_mfma_f32_16x16x32_bf16 v[114:117], v[246:249], v[174:177], v[114:117]
	ds_read_b128 v[246:249], v199 offset:4096
	v_mfma_f32_16x16x32_bf16 v[118:121], v[250:253], v[162:165], v[118:121]
	v_mfma_f32_16x16x32_bf16 v[122:125], v[250:253], v[166:169], v[122:125]
	v_mfma_f32_16x16x32_bf16 v[126:129], v[250:253], v[170:173], v[126:129]
	v_mfma_f32_16x16x32_bf16 v[2:5], v[250:253], v[174:177], v[2:5]
	ds_read_b128 v[250:253], v199 offset:6144
	global_load_dwordx4 v[162:165], v196, s[44:45] offset:384
	global_load_dwordx4 v[166:169], v208, s[44:45] offset:384
	global_load_dwordx4 v[170:173], v209, s[44:45] offset:384
	global_load_dwordx4 v[174:177], v210, s[44:45] offset:384
	global_load_dwordx4 v[178:181], v196, s[42:43] offset:384
	global_load_dwordx4 v[182:185], v208, s[42:43] offset:384
	global_load_dwordx4 v[186:189], v209, s[42:43] offset:384
	global_load_dwordx4 v[190:193], v210, s[42:43] offset:384
	s_branch .LBB0_82
; #define GCOMPUTE(AS, BS) GCOMPUTE_KS(AS, BS, 0) GCOMPUTE_KS(AS, BS, 1)
; template <int EPI>
; DI void gemm_phase(const P& p, int l, const u16* __restrict__ A, const u16* __restrict__ Bt, int mpx, char* lds) {
;     ...
;     GCOMPUTE(As0, Bs0)
;     __builtin_amdgcn_sched_barrier(0);
;   }
;   __syncthreads();
;   __builtin_amdgcn_sched_barrier(0);
;   GCOMPUTE(As1, Bs1)
;   __builtin_amdgcn_sched_barrier(0);
.Lgemm_in_exit:
	v_mfma_f32_16x16x32_bf16 v[102:105], v[246:249], v[162:165], v[102:105]
	v_mfma_f32_16x16x32_bf16 v[106:109], v[246:249], v[166:169], v[106:109]
	v_mfma_f32_16x16x32_bf16 v[110:113], v[246:249], v[170:173], v[110:113]
	v_mfma_f32_16x16x32_bf16 v[114:117], v[246:249], v[174:177], v[114:117]
	v_mfma_f32_16x16x32_bf16 v[118:121], v[250:253], v[162:165], v[118:121]
	v_mfma_f32_16x16x32_bf16 v[122:125], v[250:253], v[166:169], v[122:125]
	v_mfma_f32_16x16x32_bf16 v[126:129], v[250:253], v[170:173], v[126:129]
	v_mfma_f32_16x16x32_bf16 v[2:5], v[250:253], v[174:177], v[2:5]
	s_barrier
	ds_read_b128 v[162:165], v199
	ds_read_b128 v[166:169], v198
	ds_read_b128 v[170:173], v198 offset:2048
	ds_read_b128 v[174:177], v198 offset:4096
	ds_read_b128 v[178:181], v198 offset:6144
	s_waitcnt lgkmcnt(3)
	v_mfma_f32_16x16x32_bf16 v[6:9], v[162:165], v[166:169], v[6:9]
	s_waitcnt lgkmcnt(2)
	v_mfma_f32_16x16x32_bf16 v[10:13], v[162:165], v[170:173], v[10:13]
	s_waitcnt lgkmcnt(1)
	v_mfma_f32_16x16x32_bf16 v[14:17], v[162:165], v[174:177], v[14:17]
	s_waitcnt lgkmcnt(0)
	v_mfma_f32_16x16x32_bf16 v[18:21], v[162:165], v[178:181], v[18:21]
	ds_read_b128 v[162:165], v199 offset:2048
	s_waitcnt lgkmcnt(0)
	v_mfma_f32_16x16x32_bf16 v[22:25], v[162:165], v[166:169], v[22:25]
	v_mfma_f32_16x16x32_bf16 v[26:29], v[162:165], v[170:173], v[26:29]
	v_mfma_f32_16x16x32_bf16 v[30:33], v[162:165], v[174:177], v[30:33]
	v_mfma_f32_16x16x32_bf16 v[34:37], v[162:165], v[178:181], v[34:37]
	ds_read_b128 v[162:165], v199 offset:4096
	s_waitcnt lgkmcnt(0)
	v_mfma_f32_16x16x32_bf16 v[38:41], v[162:165], v[166:169], v[38:41]
	v_mfma_f32_16x16x32_bf16 v[42:45], v[162:165], v[170:173], v[42:45]
	v_mfma_f32_16x16x32_bf16 v[46:49], v[162:165], v[174:177], v[46:49]
	v_mfma_f32_16x16x32_bf16 v[50:53], v[162:165], v[178:181], v[50:53]
	ds_read_b128 v[162:165], v199 offset:6144
	s_waitcnt lgkmcnt(0)
	v_mfma_f32_16x16x32_bf16 v[54:57], v[162:165], v[166:169], v[54:57]
	v_mfma_f32_16x16x32_bf16 v[58:61], v[162:165], v[170:173], v[58:61]
	v_mfma_f32_16x16x32_bf16 v[62:65], v[162:165], v[174:177], v[62:65]
	v_mfma_f32_16x16x32_bf16 v[66:69], v[162:165], v[178:181], v[66:69]
	ds_read_b128 v[162:165], v199 offset:8192
	s_waitcnt lgkmcnt(0)
	v_mfma_f32_16x16x32_bf16 v[182:185], v[162:165], v[166:169], v[70:73]
	s_nop 2
	ds_read_b128 v[70:73], v199 offset:10240
	v_mfma_f32_16x16x32_bf16 v[186:189], v[162:165], v[170:173], v[74:77]
	s_nop 2
	ds_read_b128 v[74:77], v233
	s_waitcnt lgkmcnt(1)
	v_mfma_f32_16x16x32_bf16 v[212:215], v[70:73], v[166:169], v[86:89]
	v_mfma_f32_16x16x32_bf16 v[216:219], v[70:73], v[170:173], v[90:93]
	v_mfma_f32_16x16x32_bf16 v[220:223], v[70:73], v[174:177], v[94:97]
	v_mfma_f32_16x16x32_bf16 v[234:237], v[70:73], v[178:181], v[98:101]
	ds_read_b128 v[70:73], v199 offset:12288
	s_waitcnt lgkmcnt(0)
	v_mfma_f32_16x16x32_bf16 v[238:241], v[70:73], v[166:169], v[102:105]
	v_mfma_f32_16x16x32_bf16 v[242:245], v[70:73], v[170:173], v[106:109]
	v_mfma_f32_16x16x32_bf16 v[246:249], v[70:73], v[174:177], v[110:113]
	v_mfma_f32_16x16x32_bf16 v[250:253], v[70:73], v[178:181], v[114:117]
	ds_read_b128 v[70:73], v199 offset:14336
	v_mfma_f32_16x16x32_bf16 v[190:193], v[162:165], v[174:177], v[78:81]
	v_mfma_f32_16x16x32_bf16 v[162:165], v[162:165], v[178:181], v[82:85]
	s_waitcnt lgkmcnt(0)
	v_mfma_f32_16x16x32_bf16 v[178:181], v[70:73], v[178:181], v[2:5]
	s_nop 2
	ds_read_b128 v[2:5], v200
	v_mfma_f32_16x16x32_bf16 v[174:177], v[70:73], v[174:177], v[126:129]
	s_waitcnt lgkmcnt(0)
	v_mfma_f32_16x16x32_bf16 v[126:129], v[74:77], v[2:5], v[6:9]
	s_nop 2
	ds_read_b128 v[6:9], v200 offset:2048
	v_mfma_f32_16x16x32_bf16 v[170:173], v[70:73], v[170:173], v[122:125]
	s_waitcnt lgkmcnt(0)
	v_mfma_f32_16x16x32_bf16 v[122:125], v[74:77], v[6:9], v[10:13]
	s_nop 2
	ds_read_b128 v[10:13], v200 offset:4096
	v_mfma_f32_16x16x32_bf16 v[166:169], v[70:73], v[166:169], v[118:121]
	s_waitcnt lgkmcnt(0)
	v_mfma_f32_16x16x32_bf16 v[118:121], v[74:77], v[10:13], v[14:17]
	s_nop 2
	ds_read_b128 v[14:17], v200 offset:6144
	s_waitcnt lgkmcnt(0)
	v_mfma_f32_16x16x32_bf16 v[114:117], v[74:77], v[14:17], v[18:21]
	s_nop 2
	ds_read_b128 v[18:21], v233 offset:2048
	s_waitcnt lgkmcnt(0)
	v_mfma_f32_16x16x32_bf16 v[110:113], v[18:21], v[2:5], v[22:25]
	v_mfma_f32_16x16x32_bf16 v[106:109], v[18:21], v[6:9], v[26:29]
	v_mfma_f32_16x16x32_bf16 v[102:105], v[18:21], v[10:13], v[30:33]
	v_mfma_f32_16x16x32_bf16 v[98:101], v[18:21], v[14:17], v[34:37]
	ds_read_b128 v[18:21], v233 offset:4096
	s_waitcnt lgkmcnt(0)
	v_mfma_f32_16x16x32_bf16 v[94:97], v[18:21], v[2:5], v[38:41]
	v_mfma_f32_16x16x32_bf16 v[90:93], v[18:21], v[6:9], v[42:45]
	v_mfma_f32_16x16x32_bf16 v[86:89], v[18:21], v[10:13], v[46:49]
	v_mfma_f32_16x16x32_bf16 v[82:85], v[18:21], v[14:17], v[50:53]
	ds_read_b128 v[18:21], v233 offset:6144
	s_waitcnt lgkmcnt(0)
	v_mfma_f32_16x16x32_bf16 v[78:81], v[18:21], v[2:5], v[54:57]
	v_mfma_f32_16x16x32_bf16 v[74:77], v[18:21], v[6:9], v[58:61]
	v_mfma_f32_16x16x32_bf16 v[70:73], v[18:21], v[10:13], v[62:65]
	v_mfma_f32_16x16x32_bf16 v[66:69], v[18:21], v[14:17], v[66:69]
	ds_read_b128 v[18:21], v233 offset:8192
	s_waitcnt lgkmcnt(0)
	v_mfma_f32_16x16x32_bf16 v[62:65], v[18:21], v[2:5], v[182:185]
	s_nop 2
	ds_read_b128 v[182:185], v233 offset:14336
	v_mfma_f32_16x16x32_bf16 v[58:61], v[18:21], v[6:9], v[186:189]
	v_mfma_f32_16x16x32_bf16 v[54:57], v[18:21], v[10:13], v[190:193]
	v_mfma_f32_16x16x32_bf16 v[50:53], v[18:21], v[14:17], v[162:165]
	ds_read_b128 v[18:21], v233 offset:10240
	s_waitcnt lgkmcnt(0)
	v_mfma_f32_16x16x32_bf16 v[46:49], v[18:21], v[2:5], v[212:215]
	v_mfma_f32_16x16x32_bf16 v[42:45], v[18:21], v[6:9], v[216:219]
	v_mfma_f32_16x16x32_bf16 v[38:41], v[18:21], v[10:13], v[220:223]
	v_mfma_f32_16x16x32_bf16 v[34:37], v[18:21], v[14:17], v[234:237]
	ds_read_b128 v[18:21], v233 offset:12288
	s_waitcnt lgkmcnt(0)
	v_mfma_f32_16x16x32_bf16 v[30:33], v[18:21], v[2:5], v[238:241]
	v_mfma_f32_16x16x32_bf16 v[26:29], v[18:21], v[6:9], v[242:245]
	v_mfma_f32_16x16x32_bf16 v[22:25], v[18:21], v[10:13], v[246:249]
	v_mfma_f32_16x16x32_bf16 v[18:21], v[18:21], v[14:17], v[250:253]
	v_mfma_f32_16x16x32_bf16 v[166:169], v[182:185], v[2:5], v[166:169]
	v_mfma_f32_16x16x32_bf16 v[162:165], v[182:185], v[6:9], v[170:173]
	v_mfma_f32_16x16x32_bf16 v[2:5], v[182:185], v[10:13], v[174:177]
	v_mfma_f32_16x16x32_bf16 v[6:9], v[182:185], v[14:17], v[178:181]
	s_barrier
; template <int EPI>
; DI void gemm_phase(const P& p, int l, const u16* __restrict__ A, const u16* __restrict__ Bt, int mpx, char* lds) {
;     ...
;   __syncthreads();
;   GSTORE(As0, Bs0)
;     ...
;     const int cb = n0 + wn * 64;
;     const bool isctx = m0 >= MLAT;
;     const int b = isctx ? ((m0 - MLAT) >> 8) : (m0 >> 11);
;     const int tokw = (isctx ? 2048 + ((m0 - MLAT) & 255) : (m0 & 2047)) + wm * 128;
;     u16* Tl = (u16*)(lds + 65536) + w * (64 * 72);
;     int kind = 0;
;     int tr = 0;
;     bool donorm = false;
;     if (cb >= 2816) { kind = 2; tr = 1; }
;     else if (cb < 256) tr = 1;
;     else if (cb < 512) tr = 0;
;     else if (cb < 1024) tr = 2;
;     else if (cb < 1408) { tr = 3; donorm = true; }
;     else if (cb < 1536) kind = 1;
;     else if (cb < 2048) tr = isctx ? 0 : 4;
;     else if (cb < 2304) kind = 1;
;     else if (cb < 2688) tr = isctx ? 0 : 3;
;     else kind = 1;
	s_waitcnt vmcnt(7)
	ds_write_b128 v201, v[130:133]
	s_waitcnt vmcnt(5)
	ds_write_b128 v201, v[134:137] offset:8192
	s_waitcnt vmcnt(4)
	ds_write_b128 v201, v[138:141] offset:16384
	s_waitcnt vmcnt(3)
	ds_write_b128 v201, v[142:145] offset:24576
	ds_write_b128 v201, v[146:149] offset:32768
	s_waitcnt vmcnt(2)
	ds_write_b128 v201, v[150:153] offset:40960
	s_waitcnt vmcnt(1)
	ds_write_b128 v201, v[154:157] offset:49152
	s_waitcnt vmcnt(0)
	ds_write_b128 v201, v[158:161] offset:57344
	v_mov_b32_e32 v148, v195
	s_movk_i32 s0, 0xf5ff
	v_and_b32_e32 v0, 0xc0, v148
	v_add_u32_e32 v140, s46, v0
	v_mov_b32_e32 v0, 0x8000
	v_sub_co_u32_e32 v137, vcc, s66, v0
	v_add_u32_e32 v0, 0xfffff500, v140
	v_cmp_lt_u32_e64 s[40:41], s0, v0
	v_mov_b32_e32 v147, 1
	s_mov_b64 s[64:65], 0
	s_mov_b64 s[0:1], 0
	s_mov_b64 s[42:43], exec
	s_and_b64 s[40:41], s[42:43], s[40:41]
	v_mov_b32_e32 v236, 0x358637bd
	s_mov_b64 exec, s[40:41]
	s_cbranch_execz .LBB0_97
	s_movk_i32 s0, 0x1ff
	v_cmp_lt_u32_e64 s[40:41], s0, v140
	v_mov_b32_e32 v147, 0
	s_mov_b64 s[46:47], 0
	s_mov_b64 s[44:45], 0
	s_and_saveexec_b64 s[0:1], s[40:41]
	s_cbranch_execz .LBB0_96
	s_movk_i32 s2, 0x3ff
	v_cmp_lt_u32_e64 s[40:41], s2, v140
	v_mov_b32_e32 v147, 2
	s_mov_b64 s[62:63], 0
	s_and_saveexec_b64 s[44:45], s[40:41]
	s_cbranch_execz .LBB0_95
	s_movk_i32 s2, 0x57f
	v_cmp_lt_u32_e64 s[40:41], s2, v140
	s_mov_b64 s[48:49], 0
	v_mov_b32_e32 v147, 3
	s_mov_b64 s[62:63], -1
	s_and_saveexec_b64 s[46:47], s[40:41]
	s_cbranch_execz .LBB0_94
	s_movk_i32 s2, 0x5ff
	v_cmp_lt_u32_e64 s[40:41], s2, v140
	s_mov_b64 s[64:65], -1
	v_mov_b32_e32 v147, 0
	s_and_saveexec_b64 s[48:49], s[40:41]
	s_cbranch_execz .LBB0_93
	s_movk_i32 s2, 0x7ff
	v_cmp_lt_u32_e64 s[40:41], s2, v140
	s_and_saveexec_b64 s[64:65], s[40:41]
	s_xor_b64 s[40:41], exec, s[64:65]
	s_and_b64 s[62:63], vcc, exec
	s_cselect_b32 s2, 3, 0
	v_add_u32_e32 v0, 0xfffff580, v140
	v_mov_b32_e32 v10, s2
	s_movk_i32 s2, 0xfe80
	v_cmp_gt_u32_e64 s[62:63], s2, v0
	s_nop 1
	v_cndmask_b32_e64 v147, v10, 0, s[62:63]
	s_andn2_saveexec_b64 s[40:41], s[40:41]
	s_and_b64 s[64:65], vcc, exec
	s_cselect_b32 s2, 4, 0
	v_mov_b32_e32 v147, s2
	s_andn2_b64 s[62:63], s[62:63], exec
	s_or_b64 exec, exec, s[40:41]
	s_orn2_b64 s[64:65], s[62:63], exec
